# GEMM K-loop blocks: drop redundant lgkmcnt(0) and mid-block setprio pair, close barrier before last 4 MFMAs (prio 2 tail); drop loop-entry vmcnt(0) P1/P5; XB stores sc1
# speedup vs baseline: 1.0071x; 1.0071x over previous
.LBB0_90:
	s_waitcnt vmcnt(7)
	v_cvt_pk_bf16_f32 v96, v74, v75
	v_cvt_pk_bf16_f32 v97, v76, v77
	s_waitcnt vmcnt(3)
	v_cvt_pk_bf16_f32 v98, v78, v79
	v_cvt_pk_bf16_f32 v99, v80, v81
	ds_read_b128 v[108:111], v101
	ds_read_b128 v[112:115], v101 offset:4096
	v_fma_f32 v95, v77, v77, 0
	v_fma_f32 v107, v81, v81, 0
	ds_read_b128 v[116:119], v101 offset:8192
	ds_read_b128 v[120:123], v101 offset:12288
	v_fmac_f32_e32 v95, v76, v76
	v_pk_mul_f32 v[76:77], v[16:17], v[76:77]
	v_fmac_f32_e32 v107, v80, v80
	v_pk_mul_f32 v[134:135], v[16:17], v[80:81]
	v_fmac_f32_e32 v107, v79, v79
	v_pk_mul_f32 v[136:137], v[14:15], v[78:79]
	s_waitcnt lgkmcnt(3)
	v_fma_f32 v79, v77, v111, 0
	v_fma_f32 v80, v135, v111, 0
	v_pk_mul_f32 v[132:133], v[14:15], v[74:75]
	v_fmac_f32_e32 v79, v76, v110
	v_fmac_f32_e32 v80, v134, v110
	v_fmac_f32_e32 v79, v133, v109
	v_fmac_f32_e32 v80, v137, v109
	v_fmac_f32_e32 v79, v132, v108
	v_fmac_f32_e32 v80, v136, v108
	s_waitcnt lgkmcnt(2)
	v_fma_f32 v81, v77, v115, 0
	v_fma_f32 v108, v135, v115, 0
	s_waitcnt lgkmcnt(1)
	v_fma_f32 v110, v77, v119, 0
	v_fma_f32 v111, v135, v119, 0
	v_fmac_f32_e32 v81, v76, v114
	v_fmac_f32_e32 v108, v134, v114
	v_fmac_f32_e32 v110, v76, v118
	v_fmac_f32_e32 v111, v134, v118
	v_fmac_f32_e32 v81, v133, v113
	v_fmac_f32_e32 v108, v137, v113
	v_fmac_f32_e32 v110, v133, v117
	v_fmac_f32_e32 v111, v137, v117
	v_fmac_f32_e32 v81, v132, v112
	v_fmac_f32_e32 v108, v136, v112
	v_fmac_f32_e32 v110, v132, v116
	v_fmac_f32_e32 v111, v136, v116
	s_waitcnt lgkmcnt(0)
	v_fma_f32 v109, v77, v123, 0
	v_fma_f32 v112, v135, v123, 0
	ds_read_b128 v[116:119], v101 offset:16384
	v_fmac_f32_e32 v109, v76, v122
	v_fmac_f32_e32 v112, v134, v122
	v_fmac_f32_e32 v109, v133, v121
	v_fmac_f32_e32 v112, v137, v121
	v_fmac_f32_e32 v109, v132, v120
	v_fmac_f32_e32 v112, v136, v120
	ds_read_b128 v[120:123], v101 offset:20480
	s_waitcnt lgkmcnt(1)
	v_fma_f32 v113, v77, v119, 0
	v_fma_f32 v114, v135, v119, 0
	v_fmac_f32_e32 v113, v76, v118
	v_fmac_f32_e32 v114, v134, v118
	ds_read_b128 v[124:127], v101 offset:24576
	ds_read_b128 v[128:131], v101 offset:28672
	v_fmac_f32_e32 v113, v133, v117
	v_fmac_f32_e32 v114, v137, v117
	v_fmac_f32_e32 v113, v132, v116
	v_fmac_f32_e32 v114, v136, v116
	s_waitcnt lgkmcnt(2)
	v_fma_f32 v115, v77, v123, 0
	v_fma_f32 v116, v135, v123, 0
	v_fmac_f32_e32 v115, v76, v122
	v_fmac_f32_e32 v116, v134, v122
	v_fmac_f32_e32 v115, v133, v121
	v_fmac_f32_e32 v116, v137, v121
	v_fmac_f32_e32 v115, v132, v120
	v_fmac_f32_e32 v116, v136, v120
	s_waitcnt lgkmcnt(1)
	v_fma_f32 v117, v77, v127, 0
	v_fma_f32 v118, v135, v127, 0
	s_waitcnt lgkmcnt(0)
	v_fma_f32 v119, v77, v131, 0
	v_fma_f32 v120, v135, v131, 0
	v_fmac_f32_e32 v117, v76, v126
	v_fmac_f32_e32 v118, v134, v126
	v_fmac_f32_e32 v119, v76, v130
	v_fmac_f32_e32 v120, v134, v130
	v_fmac_f32_e32 v95, v75, v75
	v_fmac_f32_e32 v117, v133, v125
	v_fmac_f32_e32 v118, v137, v125
	v_fmac_f32_e32 v119, v133, v129
	v_fmac_f32_e32 v120, v137, v129
	v_fmac_f32_e32 v117, v132, v124
	v_fmac_f32_e32 v118, v136, v124
	v_fmac_f32_e32 v119, v132, v128
	v_fmac_f32_e32 v120, v136, v128
	v_fmac_f32_e32 v95, v74, v74
	v_cvt_pk_bf16_f32 v74, v66, v67
	v_cvt_pk_bf16_f32 v75, v68, v69
	s_waitcnt vmcnt(2)
	v_cvt_pk_bf16_f32 v76, v70, v71
	v_cvt_pk_bf16_f32 v77, v72, v73
	ds_read_b128 v[122:125], v101 offset:1024
	ds_read_b128 v[126:129], v101 offset:5120
	v_fmac_f32_e32 v107, v78, v78
	v_fmac_f32_e32 v95, v69, v69
	v_fmac_f32_e32 v107, v73, v73
	v_fmac_f32_e32 v95, v68, v68
	v_pk_mul_f32 v[68:69], v[12:13], v[68:69]
	v_fmac_f32_e32 v107, v72, v72
	v_pk_mul_f32 v[72:73], v[12:13], v[72:73]
	s_waitcnt lgkmcnt(1)
	v_fmac_f32_e32 v79, v69, v125
	v_fmac_f32_e32 v80, v73, v125
	s_waitcnt lgkmcnt(0)
	v_fmac_f32_e32 v81, v69, v129
	v_fmac_f32_e32 v108, v73, v129
	v_pk_mul_f32 v[130:131], v[10:11], v[66:67]
	v_pk_mul_f32 v[132:133], v[10:11], v[70:71]
	v_fmac_f32_e32 v79, v68, v124
	v_fmac_f32_e32 v80, v72, v124
	v_fmac_f32_e32 v81, v68, v128
	v_fmac_f32_e32 v108, v72, v128
	v_fmac_f32_e32 v79, v131, v123
	v_fmac_f32_e32 v80, v133, v123
	v_fmac_f32_e32 v81, v131, v127
	v_fmac_f32_e32 v108, v133, v127
	v_fmac_f32_e32 v79, v130, v122
	v_fmac_f32_e32 v80, v132, v122
	v_fmac_f32_e32 v81, v130, v126
	ds_read_b128 v[122:125], v101 offset:9216
	v_fmac_f32_e32 v108, v132, v126
	ds_read_b128 v[126:129], v101 offset:13312
	v_fmac_f32_e32 v95, v67, v67
	v_fmac_f32_e32 v107, v71, v71
	s_waitcnt lgkmcnt(1)
	v_fmac_f32_e32 v110, v69, v125
	v_fmac_f32_e32 v111, v73, v125
	s_waitcnt lgkmcnt(0)
	v_fmac_f32_e32 v109, v69, v129
	v_fmac_f32_e32 v112, v73, v129
	v_fmac_f32_e32 v110, v68, v124
	v_fmac_f32_e32 v111, v72, v124
	v_fmac_f32_e32 v109, v68, v128
	v_fmac_f32_e32 v112, v72, v128
	v_fmac_f32_e32 v110, v131, v123
	v_fmac_f32_e32 v111, v133, v123
	v_fmac_f32_e32 v109, v131, v127
	v_fmac_f32_e32 v112, v133, v127
	v_fmac_f32_e32 v110, v130, v122
	v_fmac_f32_e32 v111, v132, v122
	v_fmac_f32_e32 v109, v130, v126
	ds_read_b128 v[122:125], v101 offset:17408
	v_fmac_f32_e32 v112, v132, v126
	ds_read_b128 v[126:129], v101 offset:21504
	v_fmac_f32_e32 v95, v66, v66
	v_fmac_f32_e32 v107, v70, v70
	s_waitcnt lgkmcnt(1)
	v_fmac_f32_e32 v113, v69, v125
	v_fmac_f32_e32 v114, v73, v125
	s_waitcnt lgkmcnt(0)
	v_fmac_f32_e32 v115, v69, v129
	v_fmac_f32_e32 v116, v73, v129
	v_fmac_f32_e32 v113, v68, v124
	v_fmac_f32_e32 v114, v72, v124
	v_fmac_f32_e32 v115, v68, v128
	v_fmac_f32_e32 v116, v72, v128
	v_fmac_f32_e32 v113, v131, v123
	v_fmac_f32_e32 v114, v133, v123
	v_fmac_f32_e32 v115, v131, v127
	v_fmac_f32_e32 v116, v133, v127
	v_fmac_f32_e32 v113, v130, v122
	v_fmac_f32_e32 v114, v132, v122
	v_fmac_f32_e32 v115, v130, v126
	ds_read_b128 v[122:125], v101 offset:25600
	v_fmac_f32_e32 v116, v132, v126
	ds_read_b128 v[126:129], v101 offset:29696
	v_cvt_pk_bf16_f32 v66, v58, v59
	s_waitcnt lgkmcnt(1)
	v_fmac_f32_e32 v117, v69, v125
	v_fmac_f32_e32 v118, v73, v125
	s_waitcnt lgkmcnt(0)
	v_fmac_f32_e32 v119, v69, v129
	v_fmac_f32_e32 v120, v73, v129
	v_fmac_f32_e32 v117, v68, v124
	v_fmac_f32_e32 v118, v72, v124
	v_fmac_f32_e32 v119, v68, v128
	v_fmac_f32_e32 v120, v72, v128
	v_cvt_pk_bf16_f32 v67, v60, v61
	s_waitcnt vmcnt(1)
	v_cvt_pk_bf16_f32 v68, v62, v63
	v_cvt_pk_bf16_f32 v69, v64, v65
	ds_read_b128 v[70:73], v101 offset:2048
	v_fmac_f32_e32 v117, v131, v123
	v_fmac_f32_e32 v118, v133, v123
	v_fmac_f32_e32 v117, v130, v122
	v_fmac_f32_e32 v118, v132, v122
	ds_read_b128 v[122:125], v101 offset:6144
	v_fmac_f32_e32 v95, v61, v61
	v_fmac_f32_e32 v107, v65, v65
	v_fmac_f32_e32 v95, v60, v60
	v_pk_mul_f32 v[60:61], v[8:9], v[60:61]
	v_fmac_f32_e32 v107, v64, v64
	v_pk_mul_f32 v[64:65], v[8:9], v[64:65]
	v_fmac_f32_e32 v119, v131, v127
	v_fmac_f32_e32 v120, v133, v127
	s_waitcnt lgkmcnt(1)
	v_fmac_f32_e32 v79, v61, v73
	v_fmac_f32_e32 v80, v65, v73
	v_fmac_f32_e32 v119, v130, v126
	v_fmac_f32_e32 v120, v132, v126
	v_pk_mul_f32 v[126:127], v[6:7], v[58:59]
	v_pk_mul_f32 v[128:129], v[6:7], v[62:63]
	v_fmac_f32_e32 v79, v60, v72
	v_fmac_f32_e32 v80, v64, v72
	v_fmac_f32_e32 v79, v127, v71
	v_fmac_f32_e32 v80, v129, v71
	s_waitcnt lgkmcnt(0)
	v_fmac_f32_e32 v81, v61, v125
	v_fmac_f32_e32 v108, v65, v125
	v_fmac_f32_e32 v79, v126, v70
	v_fmac_f32_e32 v80, v128, v70
	v_fmac_f32_e32 v81, v60, v124
	ds_read_b128 v[70:73], v101 offset:10240
	v_fmac_f32_e32 v108, v64, v124
	v_fmac_f32_e32 v81, v127, v123
	v_fmac_f32_e32 v108, v129, v123
	v_fmac_f32_e32 v81, v126, v122
	v_fmac_f32_e32 v108, v128, v122
	ds_read_b128 v[122:125], v101 offset:14336
	s_waitcnt lgkmcnt(1)
	v_fmac_f32_e32 v110, v61, v73
	v_fmac_f32_e32 v111, v65, v73
	v_fmac_f32_e32 v110, v60, v72
	v_fmac_f32_e32 v111, v64, v72
	v_fmac_f32_e32 v110, v127, v71
	v_fmac_f32_e32 v111, v129, v71
	s_waitcnt lgkmcnt(0)
	v_fmac_f32_e32 v109, v61, v125
	v_fmac_f32_e32 v112, v65, v125
	v_fmac_f32_e32 v110, v126, v70
	v_fmac_f32_e32 v111, v128, v70
	v_fmac_f32_e32 v109, v60, v124
	ds_read_b128 v[70:73], v101 offset:18432
	v_fmac_f32_e32 v112, v64, v124
	v_fmac_f32_e32 v109, v127, v123
	v_fmac_f32_e32 v112, v129, v123
	v_fmac_f32_e32 v109, v126, v122
	v_fmac_f32_e32 v112, v128, v122
	ds_read_b128 v[122:125], v101 offset:22528
	s_waitcnt lgkmcnt(1)
	v_fmac_f32_e32 v113, v61, v73
	v_fmac_f32_e32 v114, v65, v73
	v_fmac_f32_e32 v113, v60, v72
	v_fmac_f32_e32 v114, v64, v72
	v_fmac_f32_e32 v113, v127, v71
	v_fmac_f32_e32 v114, v129, v71
	s_waitcnt lgkmcnt(0)
	v_fmac_f32_e32 v115, v61, v125
	v_fmac_f32_e32 v116, v65, v125
	v_fmac_f32_e32 v113, v126, v70
	v_fmac_f32_e32 v114, v128, v70
	v_fmac_f32_e32 v115, v60, v124
	ds_read_b128 v[70:73], v101 offset:26624
	v_fmac_f32_e32 v116, v64, v124
	v_fmac_f32_e32 v115, v127, v123
	v_fmac_f32_e32 v116, v129, v123
	v_fmac_f32_e32 v115, v126, v122
	v_fmac_f32_e32 v116, v128, v122
	ds_read_b128 v[122:125], v101 offset:30720
	s_waitcnt lgkmcnt(1)
	v_fmac_f32_e32 v117, v61, v73
	v_fmac_f32_e32 v118, v65, v73
	v_fmac_f32_e32 v117, v60, v72
	v_fmac_f32_e32 v118, v64, v72
	v_fmac_f32_e32 v95, v59, v59
	v_fmac_f32_e32 v107, v63, v63
	v_fmac_f32_e32 v117, v127, v71
	v_fmac_f32_e32 v118, v129, v71
	s_waitcnt lgkmcnt(0)
	v_fmac_f32_e32 v119, v61, v125
	v_fmac_f32_e32 v120, v65, v125
	v_fmac_f32_e32 v117, v126, v70
	v_fmac_f32_e32 v118, v128, v70
	v_fmac_f32_e32 v119, v60, v124
	v_fmac_f32_e32 v120, v64, v124
	v_fmac_f32_e32 v95, v58, v58
	v_fmac_f32_e32 v107, v62, v62
	v_cvt_pk_bf16_f32 v58, v54, v55
	v_cvt_pk_bf16_f32 v59, v56, v57
	s_waitcnt vmcnt(0)
	v_cvt_pk_bf16_f32 v60, v50, v51
	v_cvt_pk_bf16_f32 v61, v52, v53
	ds_read_b128 v[62:65], v101 offset:3072
	ds_read_b128 v[70:73], v101 offset:7168
	v_fmac_f32_e32 v95, v57, v57
	v_fmac_f32_e32 v107, v53, v53
	v_fmac_f32_e32 v95, v56, v56
	v_pk_mul_f32 v[56:57], v[4:5], v[56:57]
	v_fmac_f32_e32 v107, v52, v52
	v_pk_mul_f32 v[52:53], v[4:5], v[52:53]
	v_fmac_f32_e32 v119, v127, v123
	v_fmac_f32_e32 v120, v129, v123
	s_waitcnt lgkmcnt(1)
	v_fmac_f32_e32 v79, v57, v65
	v_fmac_f32_e32 v80, v53, v65
	s_waitcnt lgkmcnt(0)
	v_fmac_f32_e32 v81, v57, v73
	v_fmac_f32_e32 v108, v53, v73
	v_fmac_f32_e32 v119, v126, v122
	v_fmac_f32_e32 v120, v128, v122
	v_pk_mul_f32 v[122:123], v[2:3], v[54:55]
	v_pk_mul_f32 v[124:125], v[2:3], v[50:51]
	v_fmac_f32_e32 v79, v56, v64
	v_fmac_f32_e32 v80, v52, v64
	v_fmac_f32_e32 v81, v56, v72
	v_fmac_f32_e32 v108, v52, v72
	v_fmac_f32_e32 v79, v123, v63
	v_fmac_f32_e32 v80, v125, v63
	v_fmac_f32_e32 v81, v123, v71
	v_fmac_f32_e32 v108, v125, v71
	v_fmac_f32_e32 v79, v122, v62
	v_fmac_f32_e32 v80, v124, v62
	v_fmac_f32_e32 v81, v122, v70
	ds_read_b128 v[62:65], v101 offset:11264
	v_fmac_f32_e32 v108, v124, v70
	ds_read_b128 v[70:73], v101 offset:15360
	v_fmac_f32_e32 v107, v51, v51
	v_xor_b32_e32 v51, 1, v85
	s_waitcnt lgkmcnt(1)
	v_fmac_f32_e32 v110, v57, v65
	v_fmac_f32_e32 v111, v53, v65
	s_waitcnt lgkmcnt(0)
	v_fmac_f32_e32 v109, v57, v73
	v_fmac_f32_e32 v112, v53, v73
	v_fmac_f32_e32 v110, v56, v64
	v_fmac_f32_e32 v111, v52, v64
	v_fmac_f32_e32 v109, v56, v72
	v_fmac_f32_e32 v112, v52, v72
	v_fmac_f32_e32 v110, v123, v63
	v_fmac_f32_e32 v111, v125, v63
	v_fmac_f32_e32 v109, v123, v71
	v_fmac_f32_e32 v112, v125, v71
	v_fmac_f32_e32 v110, v122, v62
	v_fmac_f32_e32 v111, v124, v62
	v_fmac_f32_e32 v109, v122, v70
	ds_read_b128 v[62:65], v101 offset:19456
	v_fmac_f32_e32 v112, v124, v70
	ds_read_b128 v[70:73], v101 offset:23552
	v_fmac_f32_e32 v95, v55, v55
	v_cndmask_b32_e64 v55, v81, v108, s[10:11]
	s_waitcnt lgkmcnt(1)
	v_fmac_f32_e32 v113, v57, v65
	v_fmac_f32_e32 v114, v53, v65
	s_waitcnt lgkmcnt(0)
	v_fmac_f32_e32 v115, v57, v73
	v_fmac_f32_e32 v116, v53, v73
	v_fmac_f32_e32 v113, v56, v64
	v_fmac_f32_e32 v114, v52, v64
	v_fmac_f32_e32 v115, v56, v72
	v_fmac_f32_e32 v116, v52, v72
	v_fmac_f32_e32 v113, v123, v63
	v_fmac_f32_e32 v114, v125, v63
	v_fmac_f32_e32 v115, v123, v71
	v_fmac_f32_e32 v116, v125, v71
	v_fmac_f32_e32 v113, v122, v62
	v_fmac_f32_e32 v114, v124, v62
	v_fmac_f32_e32 v115, v122, v70
	ds_read_b128 v[62:65], v101 offset:27648
	v_fmac_f32_e32 v116, v124, v70
	ds_read_b128 v[70:73], v101 offset:31744
	v_fmac_f32_e32 v95, v54, v54
	v_cndmask_b32_e64 v54, v80, v79, s[10:11]
	s_waitcnt lgkmcnt(1)
	v_fmac_f32_e32 v118, v53, v65
	v_fmac_f32_e32 v118, v52, v64
	s_waitcnt lgkmcnt(0)
	v_fmac_f32_e32 v120, v53, v73
	v_fmac_f32_e32 v120, v52, v72
	v_and_b32_e32 v52, 64, v85
	v_add_u32_e32 v52, 64, v52
	v_cmp_lt_i32_e32 vcc, v51, v52
	v_cndmask_b32_e64 v53, v79, v80, s[10:11]
	v_fmac_f32_e32 v117, v57, v65
	v_cndmask_b32_e32 v51, v85, v51, vcc
	v_lshlrev_b32_e32 v51, 2, v51
	v_fmac_f32_e32 v119, v57, v73
	ds_bpermute_b32 v53, v51, v53
	v_fmac_f32_e32 v117, v56, v64
	v_fmac_f32_e32 v119, v56, v72
	ds_bpermute_b32 v55, v51, v55
	v_cndmask_b32_e64 v56, v110, v111, s[10:11]
	v_fmac_f32_e32 v117, v123, v63
	v_fmac_f32_e32 v118, v125, v63
	ds_bpermute_b32 v56, v51, v56
	v_cndmask_b32_e64 v57, v109, v112, s[10:11]
	v_fmac_f32_e32 v117, v122, v62
	v_fmac_f32_e32 v118, v124, v62
	ds_bpermute_b32 v57, v51, v57
	v_cndmask_b32_e64 v62, v113, v114, s[10:11]
	v_fmac_f32_e32 v119, v123, v71
	v_fmac_f32_e32 v120, v125, v71
	ds_bpermute_b32 v62, v51, v62
	v_cndmask_b32_e64 v63, v115, v116, s[10:11]
	v_fmac_f32_e32 v119, v122, v70
	v_fmac_f32_e32 v120, v124, v70
	s_waitcnt lgkmcnt(4)
	v_add_f32_e32 v53, v54, v53
	v_cndmask_b32_e64 v54, v108, v81, s[10:11]
	ds_bpermute_b32 v63, v51, v63
	v_cndmask_b32_e64 v64, v117, v118, s[10:11]
	s_waitcnt lgkmcnt(4)
	v_add_f32_e32 v54, v54, v55
	v_cndmask_b32_e64 v55, v111, v110, s[10:11]
	ds_bpermute_b32 v64, v51, v64
	v_cndmask_b32_e64 v65, v119, v120, s[10:11]
	s_waitcnt lgkmcnt(4)
	v_add_f32_e32 v55, v55, v56
	v_cndmask_b32_e64 v56, v112, v109, s[10:11]
	ds_bpermute_b32 v65, v51, v65
	s_waitcnt lgkmcnt(4)
	v_add_f32_e32 v56, v56, v57
	v_cndmask_b32_e64 v57, v114, v113, s[10:11]
	s_waitcnt lgkmcnt(3)
	v_add_f32_e32 v57, v57, v62
	v_cndmask_b32_e64 v62, v116, v115, s[10:11]
	s_waitcnt lgkmcnt(2)
	v_add_f32_e32 v62, v62, v63
	v_cndmask_b32_e64 v63, v118, v117, s[10:11]
	s_waitcnt lgkmcnt(1)
	v_add_f32_e32 v63, v63, v64
	v_cndmask_b32_e64 v64, v120, v119, s[10:11]
	s_waitcnt lgkmcnt(0)
	v_add_f32_e32 v64, v64, v65
	v_xor_b32_e32 v65, 2, v85
	v_cmp_lt_i32_e32 vcc, v65, v52
	v_fmac_f32_e32 v107, v50, v50
	v_cndmask_b32_e64 v50, v95, v107, s[10:11]
	v_cndmask_b32_e32 v65, v85, v65, vcc
	v_lshlrev_b32_e32 v65, 2, v65
	v_cndmask_b32_e64 v70, v53, v57, s[4:5]
	ds_bpermute_b32 v50, v51, v50
	v_cndmask_b32_e64 v51, v57, v53, s[4:5]
	v_cndmask_b32_e64 v53, v62, v54, s[4:5]
	v_cndmask_b32_e64 v54, v54, v62, s[4:5]
	ds_bpermute_b32 v54, v65, v54
	v_cndmask_b32_e64 v62, v56, v64, s[4:5]
	ds_bpermute_b32 v62, v65, v62
	v_cndmask_b32_e64 v57, v55, v63, s[4:5]
	ds_bpermute_b32 v70, v65, v70
	ds_bpermute_b32 v57, v65, v57
	s_waitcnt lgkmcnt(3)
	v_add_f32_e32 v53, v53, v54
	v_cndmask_b32_e64 v54, v63, v55, s[4:5]
	v_cndmask_b32_e64 v55, v64, v56, s[4:5]
	s_waitcnt lgkmcnt(2)
	v_add_f32_e32 v55, v55, v62
	v_cndmask_b32_e64 v62, v107, v95, s[10:11]
	v_xor_b32_e32 v56, 4, v85
	v_add_f32_e32 v50, v62, v50
	v_cmp_lt_i32_e32 vcc, v56, v52
	ds_bpermute_b32 v62, v65, v50
	s_waitcnt lgkmcnt(2)
	v_add_f32_e32 v51, v51, v70
	s_waitcnt lgkmcnt(1)
	v_add_f32_e32 v54, v54, v57
	v_cndmask_b32_e32 v56, v85, v56, vcc
	v_lshlrev_b32_e32 v56, 2, v56
	v_cndmask_b32_e64 v57, v51, v54, s[2:3]
	ds_bpermute_b32 v57, v56, v57
	v_cndmask_b32_e64 v51, v54, v51, s[2:3]
	v_cndmask_b32_e64 v54, v53, v55, s[2:3]
	s_waitcnt lgkmcnt(1)
	v_add_f32_e32 v50, v50, v62
	ds_bpermute_b32 v54, v56, v54
	ds_bpermute_b32 v56, v56, v50
	s_waitcnt lgkmcnt(2)
	v_add_f32_e32 v51, v51, v57
	v_xor_b32_e32 v57, 8, v85
	v_cmp_lt_i32_e32 vcc, v57, v52
	v_xor_b32_e32 v62, 16, v85
	s_waitcnt lgkmcnt(0)
	v_add_f32_e32 v50, v50, v56
	v_cndmask_b32_e32 v57, v85, v57, vcc
	v_lshlrev_b32_e32 v57, 2, v57
	ds_bpermute_b32 v56, v57, v50
	v_cmp_lt_i32_e32 vcc, v62, v52
	v_xor_b32_e32 v63, 32, v85
	v_cndmask_b32_e64 v53, v55, v53, s[2:3]
	v_cndmask_b32_e32 v62, v85, v62, vcc
	v_lshlrev_b32_e32 v62, 2, v62
	s_waitcnt lgkmcnt(0)
	v_add_f32_e32 v50, v50, v56
	ds_bpermute_b32 v56, v62, v50
	v_cmp_lt_i32_e32 vcc, v63, v52
	v_add_f32_e32 v53, v53, v54
	v_cndmask_b32_e64 v54, v51, v53, s[0:1]
	v_cndmask_b32_e32 v52, v85, v63, vcc
	v_lshlrev_b32_e32 v63, 2, v52
	s_waitcnt lgkmcnt(0)
	v_add_f32_e32 v50, v50, v56
	ds_bpermute_b32 v52, v63, v50
	ds_bpermute_b32 v54, v57, v54
	v_cndmask_b32_e64 v51, v53, v51, s[0:1]
	s_add_i32 s43, s20, 0xfffffe00
	s_add_i32 s21, s20, 0xffffff00
	s_waitcnt lgkmcnt(1)
	v_add_f32_e32 v50, v50, v52
	v_fmamk_f32 v50, v50, 0x3a800000, v102
	v_mul_f32_e32 v52, 0x4f800000, v50
	v_cmp_gt_f32_e32 vcc, s29, v50
	s_waitcnt lgkmcnt(0)
	v_add_f32_e32 v51, v51, v54
	ds_bpermute_b32 v53, v62, v51
	v_cndmask_b32_e32 v50, v50, v52, vcc
	v_sqrt_f32_e32 v52, v50
	s_nop 0
	v_add_u32_e32 v54, -1, v52
	v_fma_f32 v55, -v54, v52, v50
	v_cmp_ge_f32_e64 s[12:13], 0, v55
	v_add_u32_e32 v55, 1, v52
	s_nop 0
	v_cndmask_b32_e64 v54, v52, v54, s[12:13]
	v_fma_f32 v52, -v55, v52, v50
	v_cmp_lt_f32_e64 s[12:13], 0, v52
	s_nop 1
	v_cndmask_b32_e64 v52, v54, v55, s[12:13]
	v_mul_f32_e32 v54, 0x37800000, v52
	v_cndmask_b32_e32 v52, v52, v54, vcc
	v_cmp_class_f32_e32 vcc, v50, v103
	s_nop 1
	v_cndmask_b32_e32 v50, v52, v50, vcc
	v_div_scale_f32 v54, s[12:13], v50, v50, 1.0
	v_rcp_f32_e32 v55, v54
	s_waitcnt lgkmcnt(0)
	v_add_f32_e32 v52, v51, v53
	s_ashr_i32 s12, s43, 31
	s_lshr_b32 s12, s12, 20
	v_fma_f32 v51, -v54, v55, 1.0
	v_fmac_f32_e32 v55, v51, v55
	v_div_scale_f32 v51, vcc, 1.0, v50, 1.0
	v_mul_f32_e32 v56, v51, v55
	v_fma_f32 v57, -v54, v56, v51
	v_fmac_f32_e32 v56, v57, v55
	v_fma_f32 v51, -v54, v56, v51
	s_add_i32 s12, s43, s12
	v_div_fmas_f32 v51, v51, v55, v56
	s_ashr_i32 s12, s12, 12
	v_div_fixup_f32 v54, v51, v50, 1.0
	v_mad_i64_i32 v[50:51], s[12:13], s12, v105, v[90:91]
	s_ashr_i32 s12, s21, 31
	s_lshr_b32 s12, s12, 20
	ds_bpermute_b32 v53, v63, v52
	s_add_i32 s12, s21, s12
	v_add_co_u32_e32 v50, vcc, s30, v50
	s_ashr_i32 s12, s12, 12
	s_nop 0
	v_addc_co_u32_e32 v51, vcc, -1, v51, vcc
	v_mad_i64_i32 v[56:57], s[12:13], s12, v105, v[90:91]
	global_store_dwordx2 v[50:51], v[96:97], off offset:-1536 sc1
	global_store_dwordx2 v[56:57], v[98:99], off offset:-1536 sc1
	global_store_dwordx2 v[50:51], v[74:75], off offset:-1024 sc1
	global_store_dwordx2 v[56:57], v[76:77], off offset:-1024 sc1
	global_store_dwordx2 v[50:51], v[66:67], off offset:-512 sc1
	global_store_dwordx2 v[56:57], v[68:69], off offset:-512 sc1
	global_store_dwordx2 v[50:51], v[58:59], off sc1
	global_store_dwordx2 v[56:57], v[60:61], off sc1
	v_mov_b32_e32 v50, s21
	v_mov_b32_e32 v51, s43
	v_cndmask_b32_e64 v50, v50, v51, s[10:11]
	v_ashrrev_i32_e32 v51, 31, v50
	s_and_saveexec_b64 s[12:13], s[6:7]
	s_cbranch_execz .LBB0_92
	v_lshl_add_u64 v[56:57], v[50:51], 2, s[24:25]
	global_store_dword v[56:57], v54, off

.LBB0_172:
	s_add_u32 s4, s50, 0x4000000
	s_addc_u32 s5, s51, 0
	s_add_u32 s6, s50, 0x4800000
	v_readlane_b32 s8, v245, 9
	s_addc_u32 s7, s51, 0
	s_lshl_b32 s8, s8, 2
	s_add_u32 s8, s70, s8
	s_addc_u32 s9, s71, 0
	s_add_u32 s8, s8, 0xa0000
	s_addc_u32 s9, s9, 0
	s_lshl_b32 s10, s10, 5
	s_and_b32 s19, s10, 0x60
	s_mov_b64 s[10:11], 0x80
	s_add_i32 m0, s43, 0x18000
	v_lshl_add_u64 v[8:9], v[8:9], 0, s[10:11]
	s_lshl_b32 s13, s18, 13
	s_lshl_b32 s22, s19, 7
	s_waitcnt vmcnt(2)
	s_barrier
	global_load_lds_dwordx4 v[8:9], off
	v_lshl_add_u64 v[6:7], v[6:7], 0, s[10:11]
	s_add_i32 m0, s43, 0x1a000
	s_add_i32 s57, s43, 0x8000
	s_add_i32 s58, s43, 0xa000
	global_load_lds_dwordx4 v[6:7], off
	v_lshl_add_u64 v[2:3], v[2:3], 0, s[10:11]
	s_mov_b32 m0, s57
	s_add_u32 s20, s44, 0x40080
	global_load_lds_dwordx4 v[2:3], off
	v_lshl_add_u64 v[2:3], v[4:5], 0, s[10:11]
	s_mov_b32 m0, s58
	s_addc_u32 s21, s45, 0
	global_load_lds_dwordx4 v[2:3], off
	s_add_i32 m0, s43, 0x1c000
	v_lshl_add_u64 v[2:3], s[20:21], 0, v[140:141]
	global_load_lds_dwordx4 v[2:3], off
	v_lshl_add_u64 v[2:3], s[20:21], 0, v[144:145]
	s_add_i32 m0, s43, 0x1e000
	s_cmpk_lt_u32 s12, 0x100
	global_load_lds_dwordx4 v[2:3], off
	v_lshrrev_b32_e32 v3, 1, v10
	v_and_b32_e32 v3, 24, v3
	v_and_b32_e32 v2, 15, v10
	v_lshlrev_b32_e32 v4, 1, v3
	v_lshl_or_b32 v170, s18, 6, v2
	v_lshl_or_b32 v4, v2, 6, v4
	v_lshlrev_b32_e32 v2, 2, v2
	v_and_b32_e32 v5, 32, v2
	v_bitop3_b32 v6, v4, s13, v5 bitop3:0xde
	s_cselect_b64 s[12:13], -1, 0
	s_lshl_b32 s18, s18, 8
	s_add_i32 s18, s18, 0
	s_add_i32 s18, s18, 0x20400
	v_add_u32_e32 v175, s18, v2
	v_lshlrev_b32_e32 v2, 14, v11
	v_and_b32_e32 v2, 0xffff8000, v2
	v_or_b32_e32 v173, s19, v3
	v_lshl_add_u32 v2, v12, 11, v2
	v_and_b32_e32 v3, 1, v11
	v_lshl_or_b32 v2, v3, 6, v2
	v_lshl_add_u32 v146, v13, 1, v2
	v_lshlrev_b32_e32 v2, 14, v14
	v_and_b32_e32 v2, 0xffff8000, v2
	v_lshl_add_u32 v2, v15, 11, v2
	v_and_b32_e32 v3, 1, v14
	s_mov_b64 s[20:21], 0x40080
	s_waitcnt vmcnt(6)
	v_readlane_b32 s18, v245, 0
	v_lshl_or_b32 v2, v3, 6, v2
	s_bitcmp1_b32 s18, 0
	v_lshl_add_u64 v[148:149], v[146:147], 0, s[20:21]
	v_lshl_add_u32 v146, v16, 1, v2
	s_mov_b32 s59, 0
	v_bitop3_b32 v171, v4, s22, v5 bitop3:0xde
	v_and_b32_e32 v172, 63, v0
	v_or_b32_e32 v174, 0xfffffc00, v173
	s_cselect_b64 s[18:19], -1, 0
	v_lshl_add_u64 v[150:151], v[146:147], 0, s[20:21]
	s_add_i32 s60, 0, 0x10000
	s_add_i32 s61, 0, 0x14000
	v_add_u32_e32 v176, 0, v6
	s_mov_b64 s[20:21], 0x20000
	s_mov_b64 s[22:23], 0x24000
	s_mov_b64 s[24:25], 0x28000
	s_mov_b64 s[26:27], 0x2c000
	v_mov_b64_e32 v[152:153], 0x40000
	v_mov_b64_e32 v[154:155], 0x48000
	v_mov_b64_e32 v[156:157], 0x50000
	v_mov_b64_e32 v[158:159], 0x58000
	v_mov_b32_e32 v177, 0x3e38aa3b
	s_barrier
	s_branch .LBB0_175

.LBB0_178:
	v_add_u32_e32 v135, s60, v171
	s_waitcnt lgkmcnt(0)
	ds_read_b128 v[160:163], v135
	ds_read_b128 v[164:167], v135 offset:1024
	ds_read_b128 v[178:181], v135 offset:2048
	ds_read_b128 v[182:185], v135 offset:3072
	v_add_u32_e32 v135, s61, v171
	s_add_u32 s44, s0, s30
	ds_read_b128 v[186:189], v135
	ds_read_b128 v[190:193], v135 offset:1024
	ds_read_b128 v[194:197], v135 offset:2048
	ds_read_b128 v[198:201], v135 offset:3072
	s_addc_u32 s45, s1, s31
	s_add_u32 s44, s44, 0x100
	s_addc_u32 s45, s45, 0
	s_add_u32 s72, s65, s30
	s_addc_u32 s73, s66, s31
	s_cmpk_eq_i32 s30, 0x700
	s_cselect_b32 s47, s29, s45
	s_cselect_b32 s46, s62, s44
	s_cselect_b32 s45, s63, s73
	s_cselect_b32 s44, s64, s72
	v_lshl_add_u64 v[136:137], v[130:131], 0, s[30:31]
	s_add_i32 m0, s43, 0xc000
	ds_read_b128 v[202:205], v176
	ds_read_b128 v[206:209], v176 offset:1024
	ds_read_b128 v[210:213], v176 offset:2048
	ds_read_b128 v[214:217], v176 offset:3072
	ds_read_b128 v[218:221], v176 offset:4096
	ds_read_b128 v[222:225], v176 offset:5120
	ds_read_b128 v[226:229], v176 offset:6144
	ds_read_b128 v[230:233], v176 offset:7168
	global_load_lds_dwordx4 v[136:137], off
	v_lshl_add_u64 v[136:137], v[132:133], 0, s[30:31]
	s_add_i32 m0, s43, 0xe000
	s_nop 0
	global_load_lds_dwordx4 v[136:137], off
	s_waitcnt vmcnt(8)
	s_waitcnt lgkmcnt(0)
	s_barrier
	s_setprio 1
	v_mfma_f32_16x16x32_bf16 v[126:129], v[160:163], v[202:205], v[126:129]
	v_mfma_f32_16x16x32_bf16 v[122:125], v[178:181], v[202:205], v[122:125]
	v_mfma_f32_16x16x32_bf16 v[110:113], v[160:163], v[210:213], v[110:113]
	v_mfma_f32_16x16x32_bf16 v[106:109], v[178:181], v[210:213], v[106:109]
	v_mfma_f32_16x16x32_bf16 v[94:97], v[160:163], v[218:221], v[94:97]
	v_mfma_f32_16x16x32_bf16 v[90:93], v[178:181], v[218:221], v[90:93]
	v_mfma_f32_16x16x32_bf16 v[78:81], v[160:163], v[226:229], v[78:81]
	v_mfma_f32_16x16x32_bf16 v[74:77], v[178:181], v[226:229], v[74:77]
	v_mfma_f32_16x16x32_bf16 v[126:129], v[164:167], v[206:209], v[126:129]
	v_mfma_f32_16x16x32_bf16 v[122:125], v[182:185], v[206:209], v[122:125]
	v_mfma_f32_16x16x32_bf16 v[110:113], v[164:167], v[214:217], v[110:113]
	v_mfma_f32_16x16x32_bf16 v[106:109], v[182:185], v[214:217], v[106:109]
	v_mfma_f32_16x16x32_bf16 v[94:97], v[164:167], v[222:225], v[94:97]
	v_mfma_f32_16x16x32_bf16 v[90:93], v[182:185], v[222:225], v[90:93]
	v_mfma_f32_16x16x32_bf16 v[78:81], v[164:167], v[230:233], v[78:81]
	v_mfma_f32_16x16x32_bf16 v[74:77], v[182:185], v[230:233], v[74:77]
	v_mfma_f32_16x16x32_bf16 v[118:121], v[186:189], v[202:205], v[118:121]
	v_mfma_f32_16x16x32_bf16 v[114:117], v[194:197], v[202:205], v[114:117]
	v_mfma_f32_16x16x32_bf16 v[102:105], v[186:189], v[210:213], v[102:105]
	v_mfma_f32_16x16x32_bf16 v[98:101], v[194:197], v[210:213], v[98:101]
	v_mfma_f32_16x16x32_bf16 v[86:89], v[186:189], v[218:221], v[86:89]
	v_mfma_f32_16x16x32_bf16 v[82:85], v[194:197], v[218:221], v[82:85]
	v_mfma_f32_16x16x32_bf16 v[70:73], v[186:189], v[226:229], v[70:73]
	v_mfma_f32_16x16x32_bf16 v[66:69], v[194:197], v[226:229], v[66:69]
	v_mfma_f32_16x16x32_bf16 v[118:121], v[190:193], v[206:209], v[118:121]
	v_mfma_f32_16x16x32_bf16 v[114:117], v[198:201], v[206:209], v[114:117]
	v_mfma_f32_16x16x32_bf16 v[102:105], v[190:193], v[214:217], v[102:105]
	v_mfma_f32_16x16x32_bf16 v[98:101], v[198:201], v[214:217], v[98:101]
	s_setprio 2
	s_barrier
	v_mfma_f32_16x16x32_bf16 v[86:89], v[190:193], v[222:225], v[86:89]
	v_mfma_f32_16x16x32_bf16 v[82:85], v[198:201], v[222:225], v[82:85]
	v_mfma_f32_16x16x32_bf16 v[70:73], v[190:193], v[230:233], v[70:73]
	v_mfma_f32_16x16x32_bf16 v[66:69], v[198:201], v[230:233], v[66:69]
	s_setprio 0
	s_nop 0
	s_add_i32 s72, s60, s33
	v_lshl_add_u64 v[136:137], s[44:45], 0, v[140:141]
	s_mov_b32 m0, s72
	ds_read_b128 v[202:205], v176 offset:16384
	ds_read_b128 v[206:209], v176 offset:17408
	ds_read_b128 v[210:213], v176 offset:18432
	ds_read_b128 v[214:217], v176 offset:19456
	ds_read_b128 v[218:221], v176 offset:20480
	ds_read_b128 v[222:225], v176 offset:21504
	ds_read_b128 v[226:229], v176 offset:22528
	ds_read_b128 v[230:233], v176 offset:23552
	global_load_lds_dwordx4 v[136:137], off
	s_add_i32 m0, s72, 0x2000
	s_add_u32 s72, s44, 0x40000
	v_lshl_add_u64 v[168:169], s[44:45], 0, v[144:145]
	s_addc_u32 s73, s45, 0
	s_add_i32 s74, s61, s33
	global_load_lds_dwordx4 v[168:169], off
	v_lshl_add_u64 v[234:235], s[72:73], 0, v[140:141]
	s_mov_b32 m0, s74
	v_lshl_add_u64 v[236:237], s[46:47], 0, v[142:143]
	global_load_lds_dwordx4 v[234:235], off
	v_lshl_add_u64 v[234:235], s[72:73], 0, v[144:145]
	s_add_i32 m0, s74, 0x2000
	s_nop 0
	global_load_lds_dwordx4 v[234:235], off
	v_lshl_add_u64 v[234:235], s[46:47], 0, v[138:139]
	s_mov_b32 m0, s43
	s_nop 0
	global_load_lds_dwordx4 v[234:235], off
	s_mov_b32 m0, s54
	s_nop 0
	global_load_lds_dwordx4 v[236:237], off
	s_waitcnt vmcnt(8)
	s_waitcnt lgkmcnt(0)
	s_barrier
	s_setprio 1
	v_mfma_f32_16x16x32_bf16 v[62:65], v[160:163], v[202:205], v[62:65]
	v_mfma_f32_16x16x32_bf16 v[58:61], v[178:181], v[202:205], v[58:61]
	v_mfma_f32_16x16x32_bf16 v[46:49], v[160:163], v[210:213], v[46:49]
	v_mfma_f32_16x16x32_bf16 v[42:45], v[178:181], v[210:213], v[42:45]
	v_mfma_f32_16x16x32_bf16 v[30:33], v[160:163], v[218:221], v[30:33]
	v_mfma_f32_16x16x32_bf16 v[26:29], v[178:181], v[218:221], v[26:29]
	v_mfma_f32_16x16x32_bf16 v[14:17], v[160:163], v[226:229], v[14:17]
	v_mfma_f32_16x16x32_bf16 v[10:13], v[178:181], v[226:229], v[10:13]
	v_mfma_f32_16x16x32_bf16 v[62:65], v[164:167], v[206:209], v[62:65]
	v_mfma_f32_16x16x32_bf16 v[58:61], v[182:185], v[206:209], v[58:61]
	v_mfma_f32_16x16x32_bf16 v[46:49], v[164:167], v[214:217], v[46:49]
	v_mfma_f32_16x16x32_bf16 v[42:45], v[182:185], v[214:217], v[42:45]
	v_mfma_f32_16x16x32_bf16 v[30:33], v[164:167], v[222:225], v[30:33]
	v_mfma_f32_16x16x32_bf16 v[26:29], v[182:185], v[222:225], v[26:29]
	v_mfma_f32_16x16x32_bf16 v[14:17], v[164:167], v[230:233], v[14:17]
	v_mfma_f32_16x16x32_bf16 v[10:13], v[182:185], v[230:233], v[10:13]
	v_mfma_f32_16x16x32_bf16 v[54:57], v[186:189], v[202:205], v[54:57]
	v_mfma_f32_16x16x32_bf16 v[50:53], v[194:197], v[202:205], v[50:53]
	v_mfma_f32_16x16x32_bf16 v[38:41], v[186:189], v[210:213], v[38:41]
	v_mfma_f32_16x16x32_bf16 v[34:37], v[194:197], v[210:213], v[34:37]
	v_mfma_f32_16x16x32_bf16 v[22:25], v[186:189], v[218:221], v[22:25]
	v_mfma_f32_16x16x32_bf16 v[18:21], v[194:197], v[218:221], v[18:21]
	v_mfma_f32_16x16x32_bf16 v[6:9], v[186:189], v[226:229], v[6:9]
	v_mfma_f32_16x16x32_bf16 v[2:5], v[194:197], v[226:229], v[2:5]
	v_mfma_f32_16x16x32_bf16 v[54:57], v[190:193], v[206:209], v[54:57]
	v_mfma_f32_16x16x32_bf16 v[50:53], v[198:201], v[206:209], v[50:53]
	v_mfma_f32_16x16x32_bf16 v[38:41], v[190:193], v[214:217], v[38:41]
	v_mfma_f32_16x16x32_bf16 v[34:37], v[198:201], v[214:217], v[34:37]
	s_setprio 2
	s_barrier
	v_mfma_f32_16x16x32_bf16 v[22:25], v[190:193], v[222:225], v[22:25]
	v_mfma_f32_16x16x32_bf16 v[18:21], v[198:201], v[222:225], v[18:21]
	v_mfma_f32_16x16x32_bf16 v[6:9], v[190:193], v[230:233], v[6:9]
	v_mfma_f32_16x16x32_bf16 v[2:5], v[198:201], v[230:233], v[2:5]
	s_setprio 0
	s_nop 0
	s_add_i32 s72, 0, 0x18000
	v_add_u32_e32 v135, s72, v171
	s_add_i32 s73, 0, 0x1c000
	ds_read_b128 v[160:163], v135
	ds_read_b128 v[164:167], v135 offset:1024
	ds_read_b128 v[178:181], v135 offset:2048
	ds_read_b128 v[182:185], v135 offset:3072
	v_add_u32_e32 v135, s73, v171
	ds_read_b128 v[186:189], v135
	ds_read_b128 v[190:193], v135 offset:1024
	ds_read_b128 v[194:197], v135 offset:2048
	ds_read_b128 v[198:201], v135 offset:3072
	s_add_u32 s46, s46, 0x40000
	s_addc_u32 s47, s47, 0
	s_mov_b32 m0, s55
	v_lshl_add_u64 v[238:239], s[46:47], 0, v[138:139]
	ds_read_b128 v[202:205], v176 offset:32768
	ds_read_b128 v[206:209], v176 offset:33792
	ds_read_b128 v[210:213], v176 offset:34816
	ds_read_b128 v[214:217], v176 offset:35840
	ds_read_b128 v[218:221], v176 offset:36864
	ds_read_b128 v[222:225], v176 offset:37888
	ds_read_b128 v[226:229], v176 offset:38912
	ds_read_b128 v[230:233], v176 offset:39936
	global_load_lds_dwordx4 v[238:239], off
	v_lshl_add_u64 v[238:239], s[46:47], 0, v[142:143]
	s_mov_b32 m0, s56
	s_nop 0
	global_load_lds_dwordx4 v[238:239], off
	s_waitcnt vmcnt(8)
	s_waitcnt lgkmcnt(0)
	s_barrier
	s_setprio 1
	v_mfma_f32_16x16x32_bf16 v[126:129], v[160:163], v[202:205], v[126:129]
	v_mfma_f32_16x16x32_bf16 v[122:125], v[178:181], v[202:205], v[122:125]
	v_mfma_f32_16x16x32_bf16 v[110:113], v[160:163], v[210:213], v[110:113]
	v_mfma_f32_16x16x32_bf16 v[106:109], v[178:181], v[210:213], v[106:109]
	v_mfma_f32_16x16x32_bf16 v[94:97], v[160:163], v[218:221], v[94:97]
	v_mfma_f32_16x16x32_bf16 v[90:93], v[178:181], v[218:221], v[90:93]
	v_mfma_f32_16x16x32_bf16 v[78:81], v[160:163], v[226:229], v[78:81]
	v_mfma_f32_16x16x32_bf16 v[74:77], v[178:181], v[226:229], v[74:77]
	v_mfma_f32_16x16x32_bf16 v[126:129], v[164:167], v[206:209], v[126:129]
	v_mfma_f32_16x16x32_bf16 v[122:125], v[182:185], v[206:209], v[122:125]
	v_mfma_f32_16x16x32_bf16 v[110:113], v[164:167], v[214:217], v[110:113]
	v_mfma_f32_16x16x32_bf16 v[106:109], v[182:185], v[214:217], v[106:109]
	v_mfma_f32_16x16x32_bf16 v[94:97], v[164:167], v[222:225], v[94:97]
	v_mfma_f32_16x16x32_bf16 v[90:93], v[182:185], v[222:225], v[90:93]
	v_mfma_f32_16x16x32_bf16 v[78:81], v[164:167], v[230:233], v[78:81]
	v_mfma_f32_16x16x32_bf16 v[74:77], v[182:185], v[230:233], v[74:77]
	v_mfma_f32_16x16x32_bf16 v[118:121], v[186:189], v[202:205], v[118:121]
	v_mfma_f32_16x16x32_bf16 v[114:117], v[194:197], v[202:205], v[114:117]
	v_mfma_f32_16x16x32_bf16 v[102:105], v[186:189], v[210:213], v[102:105]
	v_mfma_f32_16x16x32_bf16 v[98:101], v[194:197], v[210:213], v[98:101]
	v_mfma_f32_16x16x32_bf16 v[86:89], v[186:189], v[218:221], v[86:89]
	v_mfma_f32_16x16x32_bf16 v[82:85], v[194:197], v[218:221], v[82:85]
	v_mfma_f32_16x16x32_bf16 v[70:73], v[186:189], v[226:229], v[70:73]
	v_mfma_f32_16x16x32_bf16 v[66:69], v[194:197], v[226:229], v[66:69]
	v_mfma_f32_16x16x32_bf16 v[118:121], v[190:193], v[206:209], v[118:121]
	v_mfma_f32_16x16x32_bf16 v[114:117], v[198:201], v[206:209], v[114:117]
	v_mfma_f32_16x16x32_bf16 v[102:105], v[190:193], v[214:217], v[102:105]
	v_mfma_f32_16x16x32_bf16 v[98:101], v[198:201], v[214:217], v[98:101]
	s_setprio 2
	s_barrier
	v_mfma_f32_16x16x32_bf16 v[86:89], v[190:193], v[222:225], v[86:89]
	v_mfma_f32_16x16x32_bf16 v[82:85], v[198:201], v[222:225], v[82:85]
	v_mfma_f32_16x16x32_bf16 v[70:73], v[190:193], v[230:233], v[70:73]
	v_mfma_f32_16x16x32_bf16 v[66:69], v[198:201], v[230:233], v[66:69]
	s_setprio 0
	s_nop 0
	s_add_i32 s46, s72, s33
	v_lshl_add_u64 v[136:137], v[136:137], 0, s[10:11]
	s_mov_b32 m0, s46
	ds_read_b128 v[202:205], v176 offset:49152
	ds_read_b128 v[206:209], v176 offset:50176
	ds_read_b128 v[210:213], v176 offset:51200
	ds_read_b128 v[214:217], v176 offset:52224
	ds_read_b128 v[218:221], v176 offset:53248
	ds_read_b128 v[222:225], v176 offset:54272
	ds_read_b128 v[226:229], v176 offset:55296
	ds_read_b128 v[230:233], v176 offset:56320
	global_load_lds_dwordx4 v[136:137], off
	s_add_i32 m0, s46, 0x2000
	s_add_u32 s44, s44, 0x40080
	v_lshl_add_u64 v[136:137], v[168:169], 0, s[10:11]
	s_addc_u32 s45, s45, 0
	s_add_i32 s46, s73, s33
	global_load_lds_dwordx4 v[136:137], off
	v_lshl_add_u64 v[136:137], s[44:45], 0, v[140:141]
	s_mov_b32 m0, s46
	s_nop 0
	global_load_lds_dwordx4 v[136:137], off
	v_lshl_add_u64 v[136:137], s[44:45], 0, v[144:145]
	s_add_i32 m0, s46, 0x2000
	s_nop 0
	global_load_lds_dwordx4 v[136:137], off
	v_lshl_add_u64 v[136:137], v[234:235], 0, s[10:11]
	s_mov_b32 m0, s57
	s_nop 0
	global_load_lds_dwordx4 v[136:137], off
	v_lshl_add_u64 v[136:137], v[236:237], 0, s[10:11]
	s_mov_b32 m0, s58
	s_nop 0
	global_load_lds_dwordx4 v[136:137], off
	s_waitcnt vmcnt(8)
	s_waitcnt lgkmcnt(0)
	s_barrier
	s_setprio 1
	v_mfma_f32_16x16x32_bf16 v[62:65], v[160:163], v[202:205], v[62:65]
	v_mfma_f32_16x16x32_bf16 v[58:61], v[178:181], v[202:205], v[58:61]
	v_mfma_f32_16x16x32_bf16 v[46:49], v[160:163], v[210:213], v[46:49]
	v_mfma_f32_16x16x32_bf16 v[42:45], v[178:181], v[210:213], v[42:45]
	v_mfma_f32_16x16x32_bf16 v[30:33], v[160:163], v[218:221], v[30:33]
	v_mfma_f32_16x16x32_bf16 v[26:29], v[178:181], v[218:221], v[26:29]
	v_mfma_f32_16x16x32_bf16 v[14:17], v[160:163], v[226:229], v[14:17]
	v_mfma_f32_16x16x32_bf16 v[10:13], v[178:181], v[226:229], v[10:13]
	v_mfma_f32_16x16x32_bf16 v[62:65], v[164:167], v[206:209], v[62:65]
	v_mfma_f32_16x16x32_bf16 v[58:61], v[182:185], v[206:209], v[58:61]
	v_mfma_f32_16x16x32_bf16 v[46:49], v[164:167], v[214:217], v[46:49]
	v_mfma_f32_16x16x32_bf16 v[42:45], v[182:185], v[214:217], v[42:45]
	v_mfma_f32_16x16x32_bf16 v[30:33], v[164:167], v[222:225], v[30:33]
	v_mfma_f32_16x16x32_bf16 v[26:29], v[182:185], v[222:225], v[26:29]
	v_mfma_f32_16x16x32_bf16 v[14:17], v[164:167], v[230:233], v[14:17]
	v_mfma_f32_16x16x32_bf16 v[10:13], v[182:185], v[230:233], v[10:13]
	v_mfma_f32_16x16x32_bf16 v[54:57], v[186:189], v[202:205], v[54:57]
	v_mfma_f32_16x16x32_bf16 v[50:53], v[194:197], v[202:205], v[50:53]
	v_mfma_f32_16x16x32_bf16 v[38:41], v[186:189], v[210:213], v[38:41]
	v_mfma_f32_16x16x32_bf16 v[34:37], v[194:197], v[210:213], v[34:37]
	v_mfma_f32_16x16x32_bf16 v[22:25], v[186:189], v[218:221], v[22:25]
	v_mfma_f32_16x16x32_bf16 v[18:21], v[194:197], v[218:221], v[18:21]
	v_mfma_f32_16x16x32_bf16 v[6:9], v[186:189], v[226:229], v[6:9]
	v_mfma_f32_16x16x32_bf16 v[2:5], v[194:197], v[226:229], v[2:5]
	v_mfma_f32_16x16x32_bf16 v[54:57], v[190:193], v[206:209], v[54:57]
	v_mfma_f32_16x16x32_bf16 v[50:53], v[198:201], v[206:209], v[50:53]
	v_mfma_f32_16x16x32_bf16 v[38:41], v[190:193], v[214:217], v[38:41]
	v_mfma_f32_16x16x32_bf16 v[34:37], v[198:201], v[214:217], v[34:37]
	s_setprio 2
	s_barrier
	v_mfma_f32_16x16x32_bf16 v[22:25], v[190:193], v[222:225], v[22:25]
	v_mfma_f32_16x16x32_bf16 v[18:21], v[198:201], v[222:225], v[18:21]
	v_mfma_f32_16x16x32_bf16 v[6:9], v[190:193], v[230:233], v[6:9]
	v_mfma_f32_16x16x32_bf16 v[2:5], v[198:201], v[230:233], v[2:5]
	s_setprio 0
	s_nop 0
	s_add_i32 s67, s67, 2
	s_add_u32 s30, s30, 0x100
	s_addc_u32 s31, s31, 0
	s_cmp_gt_u32 s67, 13
	s_cbranch_scc1 .LBB0_181

.LBB0_587:
	s_add_u32 s4, s36, s38
	s_addc_u32 s5, s37, s39
	s_add_u32 s4, s4, 0x100
	s_addc_u32 s5, s5, 0
	s_add_u32 s72, s65, s38
	s_addc_u32 s73, s66, s39
	s_add_i32 s74, 0, 0x10000
	v_add_u32_e32 v3, s74, v213
	ds_read_b128 v[134:137], v3
	ds_read_b128 v[138:141], v3 offset:1024
	ds_read_b128 v[142:145], v3 offset:2048
	ds_read_b128 v[146:149], v3 offset:3072
	v_add_u32_e32 v3, s63, v213
	ds_read_b128 v[150:153], v3
	ds_read_b128 v[154:157], v3 offset:1024
	ds_read_b128 v[158:161], v3 offset:2048
	ds_read_b128 v[162:165], v3 offset:3072
	s_cmpk_eq_i32 s38, 0x700
	s_cselect_b32 s41, s3, s5
	s_cselect_b32 s40, s23, s4
	s_cselect_b32 s5, s25, s73
	s_cselect_b32 s4, s64, s72
	v_lshl_add_u64 v[4:5], v[170:171], 0, s[38:39]
	s_add_i32 m0, s31, 0xc000
	ds_read_b128 v[166:169], v217
	ds_read_b128 v[176:179], v217 offset:1024
	ds_read_b128 v[180:183], v217 offset:2048
	ds_read_b128 v[184:187], v217 offset:3072
	ds_read_b128 v[188:191], v217 offset:4096
	ds_read_b128 v[192:195], v217 offset:5120
	ds_read_b128 v[218:221], v217 offset:6144
	ds_read_b128 v[222:225], v217 offset:7168
	global_load_lds_dwordx4 v[4:5], off
	v_lshl_add_u64 v[4:5], v[172:173], 0, s[38:39]
	s_add_i32 m0, s31, 0xe000
	s_nop 0
	global_load_lds_dwordx4 v[4:5], off
	s_waitcnt vmcnt(8)
	s_waitcnt lgkmcnt(0)
	s_barrier
	s_setprio 1
	v_mfma_f32_16x16x32_bf16 v[130:133], v[134:137], v[166:169], v[130:133]
	v_mfma_f32_16x16x32_bf16 v[126:129], v[142:145], v[166:169], v[126:129]
	v_mfma_f32_16x16x32_bf16 v[114:117], v[134:137], v[180:183], v[114:117]
	v_mfma_f32_16x16x32_bf16 v[110:113], v[142:145], v[180:183], v[110:113]
	v_mfma_f32_16x16x32_bf16 v[98:101], v[134:137], v[188:191], v[98:101]
	v_mfma_f32_16x16x32_bf16 v[94:97], v[142:145], v[188:191], v[94:97]
	v_mfma_f32_16x16x32_bf16 v[82:85], v[134:137], v[218:221], v[82:85]
	v_mfma_f32_16x16x32_bf16 v[78:81], v[142:145], v[218:221], v[78:81]
	v_mfma_f32_16x16x32_bf16 v[130:133], v[138:141], v[176:179], v[130:133]
	v_mfma_f32_16x16x32_bf16 v[126:129], v[146:149], v[176:179], v[126:129]
	v_mfma_f32_16x16x32_bf16 v[114:117], v[138:141], v[184:187], v[114:117]
	v_mfma_f32_16x16x32_bf16 v[110:113], v[146:149], v[184:187], v[110:113]
	v_mfma_f32_16x16x32_bf16 v[98:101], v[138:141], v[192:195], v[98:101]
	v_mfma_f32_16x16x32_bf16 v[94:97], v[146:149], v[192:195], v[94:97]
	v_mfma_f32_16x16x32_bf16 v[82:85], v[138:141], v[222:225], v[82:85]
	v_mfma_f32_16x16x32_bf16 v[78:81], v[146:149], v[222:225], v[78:81]
	v_mfma_f32_16x16x32_bf16 v[122:125], v[150:153], v[166:169], v[122:125]
	v_mfma_f32_16x16x32_bf16 v[118:121], v[158:161], v[166:169], v[118:121]
	v_mfma_f32_16x16x32_bf16 v[106:109], v[150:153], v[180:183], v[106:109]
	v_mfma_f32_16x16x32_bf16 v[102:105], v[158:161], v[180:183], v[102:105]
	v_mfma_f32_16x16x32_bf16 v[90:93], v[150:153], v[188:191], v[90:93]
	v_mfma_f32_16x16x32_bf16 v[86:89], v[158:161], v[188:191], v[86:89]
	v_mfma_f32_16x16x32_bf16 v[74:77], v[150:153], v[218:221], v[74:77]
	v_mfma_f32_16x16x32_bf16 v[70:73], v[158:161], v[218:221], v[70:73]
	v_mfma_f32_16x16x32_bf16 v[122:125], v[154:157], v[176:179], v[122:125]
	v_mfma_f32_16x16x32_bf16 v[118:121], v[162:165], v[176:179], v[118:121]
	v_mfma_f32_16x16x32_bf16 v[106:109], v[154:157], v[184:187], v[106:109]
	v_mfma_f32_16x16x32_bf16 v[102:105], v[162:165], v[184:187], v[102:105]
	s_setprio 2
	s_barrier
	v_mfma_f32_16x16x32_bf16 v[90:93], v[154:157], v[192:195], v[90:93]
	v_mfma_f32_16x16x32_bf16 v[86:89], v[162:165], v[192:195], v[86:89]
	v_mfma_f32_16x16x32_bf16 v[74:77], v[154:157], v[222:225], v[74:77]
	v_mfma_f32_16x16x32_bf16 v[70:73], v[162:165], v[222:225], v[70:73]
	s_setprio 0
	s_nop 0
	s_add_i32 s72, s74, s33
	v_lshl_add_u64 v[196:197], s[4:5], 0, v[200:201]
	s_mov_b32 m0, s72
	ds_read_b128 v[166:169], v217 offset:16384
	ds_read_b128 v[176:179], v217 offset:17408
	ds_read_b128 v[180:183], v217 offset:18432
	ds_read_b128 v[184:187], v217 offset:19456
	ds_read_b128 v[188:191], v217 offset:20480
	ds_read_b128 v[192:195], v217 offset:21504
	ds_read_b128 v[218:221], v217 offset:22528
	ds_read_b128 v[222:225], v217 offset:23552
	global_load_lds_dwordx4 v[196:197], off
	s_add_i32 m0, s72, 0x2000
	s_add_u32 s72, s4, 0x40000
	v_lshl_add_u64 v[210:211], s[4:5], 0, v[204:205]
	s_addc_u32 s73, s5, 0
	s_add_i32 s74, s63, s33
	global_load_lds_dwordx4 v[210:211], off
	v_lshl_add_u64 v[4:5], s[72:73], 0, v[200:201]
	s_mov_b32 m0, s74
	v_lshl_add_u64 v[226:227], s[40:41], 0, v[198:199]
	global_load_lds_dwordx4 v[4:5], off
	v_lshl_add_u64 v[4:5], s[72:73], 0, v[204:205]
	s_add_i32 m0, s74, 0x2000
	v_lshl_add_u64 v[230:231], s[40:41], 0, v[202:203]
	global_load_lds_dwordx4 v[4:5], off
	s_mov_b32 m0, s31
	s_nop 0
	global_load_lds_dwordx4 v[226:227], off
	s_mov_b32 m0, s42
	s_nop 0
	global_load_lds_dwordx4 v[230:231], off
	s_waitcnt vmcnt(8)
	s_waitcnt lgkmcnt(0)
	s_barrier
	s_setprio 1
	v_mfma_f32_16x16x32_bf16 v[66:69], v[134:137], v[166:169], v[66:69]
	v_mfma_f32_16x16x32_bf16 v[62:65], v[142:145], v[166:169], v[62:65]
	v_mfma_f32_16x16x32_bf16 v[50:53], v[134:137], v[180:183], v[50:53]
	v_mfma_f32_16x16x32_bf16 v[46:49], v[142:145], v[180:183], v[46:49]
	v_mfma_f32_16x16x32_bf16 v[34:37], v[134:137], v[188:191], v[34:37]
	v_mfma_f32_16x16x32_bf16 v[30:33], v[142:145], v[188:191], v[30:33]
	v_mfma_f32_16x16x32_bf16 v[18:21], v[134:137], v[218:221], v[18:21]
	v_mfma_f32_16x16x32_bf16 v[14:17], v[142:145], v[218:221], v[14:17]
	v_mfma_f32_16x16x32_bf16 v[66:69], v[138:141], v[176:179], v[66:69]
	v_mfma_f32_16x16x32_bf16 v[62:65], v[146:149], v[176:179], v[62:65]
	v_mfma_f32_16x16x32_bf16 v[50:53], v[138:141], v[184:187], v[50:53]
	v_mfma_f32_16x16x32_bf16 v[46:49], v[146:149], v[184:187], v[46:49]
	v_mfma_f32_16x16x32_bf16 v[34:37], v[138:141], v[192:195], v[34:37]
	v_mfma_f32_16x16x32_bf16 v[30:33], v[146:149], v[192:195], v[30:33]
	v_mfma_f32_16x16x32_bf16 v[18:21], v[138:141], v[222:225], v[18:21]
	v_mfma_f32_16x16x32_bf16 v[14:17], v[146:149], v[222:225], v[14:17]
	v_mfma_f32_16x16x32_bf16 v[58:61], v[150:153], v[166:169], v[58:61]
	v_mfma_f32_16x16x32_bf16 v[54:57], v[158:161], v[166:169], v[54:57]
	v_mfma_f32_16x16x32_bf16 v[42:45], v[150:153], v[180:183], v[42:45]
	v_mfma_f32_16x16x32_bf16 v[38:41], v[158:161], v[180:183], v[38:41]
	v_mfma_f32_16x16x32_bf16 v[26:29], v[150:153], v[188:191], v[26:29]
	v_mfma_f32_16x16x32_bf16 v[22:25], v[158:161], v[188:191], v[22:25]
	v_mfma_f32_16x16x32_bf16 v[10:13], v[150:153], v[218:221], v[10:13]
	v_mfma_f32_16x16x32_bf16 v[4:7], v[158:161], v[218:221], v[6:9]
	v_mfma_f32_16x16x32_bf16 v[58:61], v[154:157], v[176:179], v[58:61]
	v_mfma_f32_16x16x32_bf16 v[54:57], v[162:165], v[176:179], v[54:57]
	v_mfma_f32_16x16x32_bf16 v[42:45], v[154:157], v[184:187], v[42:45]
	v_mfma_f32_16x16x32_bf16 v[38:41], v[162:165], v[184:187], v[38:41]
	s_setprio 2
	s_barrier
	v_mfma_f32_16x16x32_bf16 v[26:29], v[154:157], v[192:195], v[26:29]
	v_mfma_f32_16x16x32_bf16 v[22:25], v[162:165], v[192:195], v[22:25]
	v_mfma_f32_16x16x32_bf16 v[10:13], v[154:157], v[222:225], v[10:13]
	v_mfma_f32_16x16x32_bf16 v[4:7], v[162:165], v[222:225], v[4:7]
	s_setprio 0
	s_nop 0
	s_add_i32 s72, 0, 0x18000
	v_add_u32_e32 v3, s72, v213
	s_add_i32 s73, 0, 0x1c000
	ds_read_b128 v[134:137], v3
	ds_read_b128 v[138:141], v3 offset:1024
	ds_read_b128 v[142:145], v3 offset:2048
	ds_read_b128 v[146:149], v3 offset:3072
	v_add_u32_e32 v3, s73, v213
	ds_read_b128 v[150:153], v3
	ds_read_b128 v[154:157], v3 offset:1024
	ds_read_b128 v[158:161], v3 offset:2048
	ds_read_b128 v[162:165], v3 offset:3072
	s_add_u32 s40, s40, 0x40000
	s_addc_u32 s41, s41, 0
	s_mov_b32 m0, s43
	v_lshl_add_u64 v[8:9], s[40:41], 0, v[198:199]
	ds_read_b128 v[166:169], v217 offset:32768
	ds_read_b128 v[176:179], v217 offset:33792
	ds_read_b128 v[180:183], v217 offset:34816
	ds_read_b128 v[184:187], v217 offset:35840
	ds_read_b128 v[188:191], v217 offset:36864
	ds_read_b128 v[192:195], v217 offset:37888
	ds_read_b128 v[218:221], v217 offset:38912
	ds_read_b128 v[222:225], v217 offset:39936
	global_load_lds_dwordx4 v[8:9], off
	v_lshl_add_u64 v[8:9], s[40:41], 0, v[202:203]
	s_mov_b32 m0, s44
	s_nop 0
	global_load_lds_dwordx4 v[8:9], off
	s_waitcnt vmcnt(8)
	s_waitcnt lgkmcnt(0)
	s_barrier
	s_setprio 1
	v_mfma_f32_16x16x32_bf16 v[130:133], v[134:137], v[166:169], v[130:133]
	v_mfma_f32_16x16x32_bf16 v[126:129], v[142:145], v[166:169], v[126:129]
	v_mfma_f32_16x16x32_bf16 v[114:117], v[134:137], v[180:183], v[114:117]
	v_mfma_f32_16x16x32_bf16 v[110:113], v[142:145], v[180:183], v[110:113]
	v_mfma_f32_16x16x32_bf16 v[98:101], v[134:137], v[188:191], v[98:101]
	v_mfma_f32_16x16x32_bf16 v[94:97], v[142:145], v[188:191], v[94:97]
	v_mfma_f32_16x16x32_bf16 v[82:85], v[134:137], v[218:221], v[82:85]
	v_mfma_f32_16x16x32_bf16 v[78:81], v[142:145], v[218:221], v[78:81]
	v_mfma_f32_16x16x32_bf16 v[130:133], v[138:141], v[176:179], v[130:133]
	v_mfma_f32_16x16x32_bf16 v[126:129], v[146:149], v[176:179], v[126:129]
	v_mfma_f32_16x16x32_bf16 v[114:117], v[138:141], v[184:187], v[114:117]
	v_mfma_f32_16x16x32_bf16 v[110:113], v[146:149], v[184:187], v[110:113]
	v_mfma_f32_16x16x32_bf16 v[98:101], v[138:141], v[192:195], v[98:101]
	v_mfma_f32_16x16x32_bf16 v[94:97], v[146:149], v[192:195], v[94:97]
	v_mfma_f32_16x16x32_bf16 v[82:85], v[138:141], v[222:225], v[82:85]
	v_mfma_f32_16x16x32_bf16 v[78:81], v[146:149], v[222:225], v[78:81]
	v_mfma_f32_16x16x32_bf16 v[122:125], v[150:153], v[166:169], v[122:125]
	v_mfma_f32_16x16x32_bf16 v[118:121], v[158:161], v[166:169], v[118:121]
	v_mfma_f32_16x16x32_bf16 v[106:109], v[150:153], v[180:183], v[106:109]
	v_mfma_f32_16x16x32_bf16 v[102:105], v[158:161], v[180:183], v[102:105]
	v_mfma_f32_16x16x32_bf16 v[90:93], v[150:153], v[188:191], v[90:93]
	v_mfma_f32_16x16x32_bf16 v[86:89], v[158:161], v[188:191], v[86:89]
	v_mfma_f32_16x16x32_bf16 v[74:77], v[150:153], v[218:221], v[74:77]
	v_mfma_f32_16x16x32_bf16 v[70:73], v[158:161], v[218:221], v[70:73]
	v_mfma_f32_16x16x32_bf16 v[122:125], v[154:157], v[176:179], v[122:125]
	v_mfma_f32_16x16x32_bf16 v[118:121], v[162:165], v[176:179], v[118:121]
	v_mfma_f32_16x16x32_bf16 v[106:109], v[154:157], v[184:187], v[106:109]
	v_mfma_f32_16x16x32_bf16 v[102:105], v[162:165], v[184:187], v[102:105]
	s_setprio 2
	s_barrier
	v_mfma_f32_16x16x32_bf16 v[90:93], v[154:157], v[192:195], v[90:93]
	v_mfma_f32_16x16x32_bf16 v[86:89], v[162:165], v[192:195], v[86:89]
	v_mfma_f32_16x16x32_bf16 v[74:77], v[154:157], v[222:225], v[74:77]
	v_mfma_f32_16x16x32_bf16 v[70:73], v[162:165], v[222:225], v[70:73]
	s_setprio 0
	s_nop 0
	s_add_i32 s40, s72, s33
	v_lshl_add_u64 v[8:9], v[196:197], 0, s[10:11]
	s_mov_b32 m0, s40
	ds_read_b128 v[166:169], v217 offset:49152
	ds_read_b128 v[176:179], v217 offset:50176
	ds_read_b128 v[180:183], v217 offset:51200
	ds_read_b128 v[184:187], v217 offset:52224
	ds_read_b128 v[188:191], v217 offset:53248
	ds_read_b128 v[192:195], v217 offset:54272
	ds_read_b128 v[218:221], v217 offset:55296
	ds_read_b128 v[222:225], v217 offset:56320
	global_load_lds_dwordx4 v[8:9], off
	s_add_i32 m0, s40, 0x2000
	s_add_u32 s4, s4, 0x40080
	v_lshl_add_u64 v[8:9], v[210:211], 0, s[10:11]
	s_addc_u32 s5, s5, 0
	s_add_i32 s40, s73, s33
	global_load_lds_dwordx4 v[8:9], off
	v_lshl_add_u64 v[8:9], s[4:5], 0, v[200:201]
	s_mov_b32 m0, s40
	s_nop 0
	global_load_lds_dwordx4 v[8:9], off
	v_lshl_add_u64 v[8:9], s[4:5], 0, v[204:205]
	s_add_i32 m0, s40, 0x2000
	s_nop 0
	global_load_lds_dwordx4 v[8:9], off
	v_lshl_add_u64 v[8:9], v[226:227], 0, s[10:11]
	s_mov_b32 m0, s47
	s_nop 0
	global_load_lds_dwordx4 v[8:9], off
	v_lshl_add_u64 v[8:9], v[230:231], 0, s[10:11]
	s_mov_b32 m0, s48
	s_nop 0
	global_load_lds_dwordx4 v[8:9], off
	s_waitcnt vmcnt(8)
	s_waitcnt lgkmcnt(0)
	s_barrier
	s_setprio 1
	v_mfma_f32_16x16x32_bf16 v[66:69], v[134:137], v[166:169], v[66:69]
	v_mfma_f32_16x16x32_bf16 v[62:65], v[142:145], v[166:169], v[62:65]
	v_mfma_f32_16x16x32_bf16 v[50:53], v[134:137], v[180:183], v[50:53]
	v_mfma_f32_16x16x32_bf16 v[46:49], v[142:145], v[180:183], v[46:49]
	v_mfma_f32_16x16x32_bf16 v[34:37], v[134:137], v[188:191], v[34:37]
	v_mfma_f32_16x16x32_bf16 v[30:33], v[142:145], v[188:191], v[30:33]
	v_mfma_f32_16x16x32_bf16 v[18:21], v[134:137], v[218:221], v[18:21]
	v_mfma_f32_16x16x32_bf16 v[14:17], v[142:145], v[218:221], v[14:17]
	v_mfma_f32_16x16x32_bf16 v[66:69], v[138:141], v[176:179], v[66:69]
	v_mfma_f32_16x16x32_bf16 v[62:65], v[146:149], v[176:179], v[62:65]
	v_mfma_f32_16x16x32_bf16 v[50:53], v[138:141], v[184:187], v[50:53]
	v_mfma_f32_16x16x32_bf16 v[46:49], v[146:149], v[184:187], v[46:49]
	v_mfma_f32_16x16x32_bf16 v[34:37], v[138:141], v[192:195], v[34:37]
	v_mfma_f32_16x16x32_bf16 v[30:33], v[146:149], v[192:195], v[30:33]
	v_mfma_f32_16x16x32_bf16 v[18:21], v[138:141], v[222:225], v[18:21]
	v_mfma_f32_16x16x32_bf16 v[14:17], v[146:149], v[222:225], v[14:17]
	v_mfma_f32_16x16x32_bf16 v[58:61], v[150:153], v[166:169], v[58:61]
	v_mfma_f32_16x16x32_bf16 v[54:57], v[158:161], v[166:169], v[54:57]
	v_mfma_f32_16x16x32_bf16 v[42:45], v[150:153], v[180:183], v[42:45]
	v_mfma_f32_16x16x32_bf16 v[38:41], v[158:161], v[180:183], v[38:41]
	v_mfma_f32_16x16x32_bf16 v[26:29], v[150:153], v[188:191], v[26:29]
	v_mfma_f32_16x16x32_bf16 v[22:25], v[158:161], v[188:191], v[22:25]
	v_mfma_f32_16x16x32_bf16 v[8:11], v[150:153], v[218:221], v[10:13]
	v_mfma_f32_16x16x32_bf16 v[4:7], v[158:161], v[218:221], v[4:7]
	v_mfma_f32_16x16x32_bf16 v[58:61], v[154:157], v[176:179], v[58:61]
	v_mfma_f32_16x16x32_bf16 v[54:57], v[162:165], v[176:179], v[54:57]
	v_mfma_f32_16x16x32_bf16 v[42:45], v[154:157], v[184:187], v[42:45]
	v_mfma_f32_16x16x32_bf16 v[38:41], v[162:165], v[184:187], v[38:41]
	s_setprio 2
	s_barrier
	v_mfma_f32_16x16x32_bf16 v[26:29], v[154:157], v[192:195], v[26:29]
	v_mfma_f32_16x16x32_bf16 v[22:25], v[162:165], v[192:195], v[22:25]
	v_mfma_f32_16x16x32_bf16 v[10:13], v[154:157], v[222:225], v[8:11]
	v_mfma_f32_16x16x32_bf16 v[6:9], v[162:165], v[222:225], v[4:7]
	s_setprio 0
	s_nop 0
	s_add_i32 s67, s67, 2
	s_add_u32 s38, s38, 0x100
	s_addc_u32 s39, s39, 0
	s_cmp_gt_u32 s67, 13
	s_cbranch_scc1 .LBB0_590

.LBB0_760:
	ds_read_b128 v[114:117], v232
	ds_read_b128 v[118:121], v232 offset:1024
	ds_read_b128 v[130:133], v232 offset:2048
	ds_read_b128 v[138:141], v232 offset:3072
	ds_read_b128 v[146:149], v233
	ds_read_b128 v[150:153], v233 offset:1024
	ds_read_b128 v[154:157], v233 offset:2048
	ds_read_b128 v[158:161], v233 offset:3072
	s_add_u32 s30, s28, 0xfffc0080
	s_addc_u32 s31, s29, -1
	s_cmp_eq_u32 s47, 12
	s_cselect_b32 s35, s3, s31
	s_cselect_b32 s34, s17, s30
	s_cselect_b32 s31, s19, s46
	s_cselect_b32 s30, s27, s45
	v_lshl_add_u64 v[206:207], s[28:29], 0, v[202:203]
	s_add_i32 m0, s36, 0xc000
	ds_read_b128 v[162:165], v234
	ds_read_b128 v[166:169], v234 offset:1024
	ds_read_b128 v[170:173], v234 offset:2048
	ds_read_b128 v[174:177], v234 offset:3072
	ds_read_b128 v[178:181], v234 offset:4096
	ds_read_b128 v[182:185], v234 offset:5120
	ds_read_b128 v[186:189], v234 offset:6144
	ds_read_b128 v[190:193], v234 offset:7168
	global_load_lds_dwordx4 v[206:207], off
	v_lshl_add_u64 v[206:207], s[28:29], 0, v[204:205]
	s_add_i32 m0, s36, 0xe000
	s_nop 0
	global_load_lds_dwordx4 v[206:207], off
	s_waitcnt vmcnt(8)
	s_waitcnt lgkmcnt(0)
	s_barrier
	s_setprio 1
	v_mfma_f32_16x16x32_bf16 v[142:145], v[114:117], v[162:165], v[142:145]
	v_mfma_f32_16x16x32_bf16 v[134:137], v[130:133], v[162:165], v[134:137]
	v_mfma_f32_16x16x32_bf16 v[110:113], v[114:117], v[170:173], v[110:113]
	v_mfma_f32_16x16x32_bf16 v[106:109], v[130:133], v[170:173], v[106:109]
	v_mfma_f32_16x16x32_bf16 v[94:97], v[114:117], v[178:181], v[94:97]
	v_mfma_f32_16x16x32_bf16 v[90:93], v[130:133], v[178:181], v[90:93]
	v_mfma_f32_16x16x32_bf16 v[78:81], v[114:117], v[186:189], v[78:81]
	v_mfma_f32_16x16x32_bf16 v[74:77], v[130:133], v[186:189], v[74:77]
	v_mfma_f32_16x16x32_bf16 v[142:145], v[118:121], v[166:169], v[142:145]
	v_mfma_f32_16x16x32_bf16 v[134:137], v[138:141], v[166:169], v[134:137]
	v_mfma_f32_16x16x32_bf16 v[110:113], v[118:121], v[174:177], v[110:113]
	v_mfma_f32_16x16x32_bf16 v[106:109], v[138:141], v[174:177], v[106:109]
	v_mfma_f32_16x16x32_bf16 v[94:97], v[118:121], v[182:185], v[94:97]
	v_mfma_f32_16x16x32_bf16 v[90:93], v[138:141], v[182:185], v[90:93]
	v_mfma_f32_16x16x32_bf16 v[78:81], v[118:121], v[190:193], v[78:81]
	v_mfma_f32_16x16x32_bf16 v[74:77], v[138:141], v[190:193], v[74:77]
	v_mfma_f32_16x16x32_bf16 v[126:129], v[146:149], v[162:165], v[126:129]
	v_mfma_f32_16x16x32_bf16 v[122:125], v[154:157], v[162:165], v[122:125]
	v_mfma_f32_16x16x32_bf16 v[102:105], v[146:149], v[170:173], v[102:105]
	v_mfma_f32_16x16x32_bf16 v[98:101], v[154:157], v[170:173], v[98:101]
	v_mfma_f32_16x16x32_bf16 v[86:89], v[146:149], v[178:181], v[86:89]
	v_mfma_f32_16x16x32_bf16 v[82:85], v[154:157], v[178:181], v[82:85]
	v_mfma_f32_16x16x32_bf16 v[70:73], v[146:149], v[186:189], v[70:73]
	v_mfma_f32_16x16x32_bf16 v[66:69], v[154:157], v[186:189], v[66:69]
	v_mfma_f32_16x16x32_bf16 v[126:129], v[150:153], v[166:169], v[126:129]
	v_mfma_f32_16x16x32_bf16 v[122:125], v[158:161], v[166:169], v[122:125]
	v_mfma_f32_16x16x32_bf16 v[102:105], v[150:153], v[174:177], v[102:105]
	v_mfma_f32_16x16x32_bf16 v[98:101], v[158:161], v[174:177], v[98:101]
	s_setprio 2
	s_barrier
	v_mfma_f32_16x16x32_bf16 v[86:89], v[150:153], v[182:185], v[86:89]
	v_mfma_f32_16x16x32_bf16 v[82:85], v[158:161], v[182:185], v[82:85]
	v_mfma_f32_16x16x32_bf16 v[70:73], v[150:153], v[190:193], v[70:73]
	v_mfma_f32_16x16x32_bf16 v[66:69], v[158:161], v[190:193], v[66:69]
	s_setprio 0
	s_nop 0
	s_add_i32 s48, s43, s33
	v_lshl_add_u64 v[206:207], s[30:31], 0, v[196:197]
	s_mov_b32 m0, s48
	ds_read_b128 v[162:165], v234 offset:16384
	ds_read_b128 v[166:169], v234 offset:17408
	ds_read_b128 v[170:173], v234 offset:18432
	ds_read_b128 v[174:177], v234 offset:19456
	ds_read_b128 v[178:181], v234 offset:20480
	ds_read_b128 v[182:185], v234 offset:21504
	ds_read_b128 v[186:189], v234 offset:22528
	ds_read_b128 v[190:193], v234 offset:23552
	global_load_lds_dwordx4 v[206:207], off
	s_add_i32 m0, s48, 0x2000
	s_add_u32 s48, s30, 0x40000
	v_lshl_add_u64 v[208:209], s[30:31], 0, v[200:201]
	s_addc_u32 s49, s31, 0
	s_add_i32 s50, s44, s33
	global_load_lds_dwordx4 v[208:209], off
	v_lshl_add_u64 v[210:211], s[48:49], 0, v[196:197]
	s_mov_b32 m0, s50
	v_lshl_add_u64 v[212:213], s[34:35], 0, v[198:199]
	global_load_lds_dwordx4 v[210:211], off
	v_lshl_add_u64 v[210:211], s[48:49], 0, v[200:201]
	s_add_i32 m0, s50, 0x2000
	s_nop 0
	global_load_lds_dwordx4 v[210:211], off
	v_lshl_add_u64 v[210:211], s[34:35], 0, v[194:195]
	s_mov_b32 m0, s36
	s_nop 0
	global_load_lds_dwordx4 v[210:211], off
	s_mov_b32 m0, s37
	s_nop 0
	global_load_lds_dwordx4 v[212:213], off
	s_waitcnt vmcnt(8)
	s_waitcnt lgkmcnt(0)
	s_barrier
	s_setprio 1
	v_mfma_f32_16x16x32_bf16 v[62:65], v[114:117], v[162:165], v[62:65]
	v_mfma_f32_16x16x32_bf16 v[58:61], v[130:133], v[162:165], v[58:61]
	v_mfma_f32_16x16x32_bf16 v[46:49], v[114:117], v[170:173], v[46:49]
	v_mfma_f32_16x16x32_bf16 v[42:45], v[130:133], v[170:173], v[42:45]
	v_mfma_f32_16x16x32_bf16 v[30:33], v[114:117], v[178:181], v[30:33]
	v_mfma_f32_16x16x32_bf16 v[26:29], v[130:133], v[178:181], v[26:29]
	v_mfma_f32_16x16x32_bf16 v[14:17], v[114:117], v[186:189], v[14:17]
	v_mfma_f32_16x16x32_bf16 v[10:13], v[130:133], v[186:189], v[10:13]
	v_mfma_f32_16x16x32_bf16 v[62:65], v[118:121], v[166:169], v[62:65]
	v_mfma_f32_16x16x32_bf16 v[58:61], v[138:141], v[166:169], v[58:61]
	v_mfma_f32_16x16x32_bf16 v[46:49], v[118:121], v[174:177], v[46:49]
	v_mfma_f32_16x16x32_bf16 v[42:45], v[138:141], v[174:177], v[42:45]
	v_mfma_f32_16x16x32_bf16 v[30:33], v[118:121], v[182:185], v[30:33]
	v_mfma_f32_16x16x32_bf16 v[26:29], v[138:141], v[182:185], v[26:29]
	v_mfma_f32_16x16x32_bf16 v[14:17], v[118:121], v[190:193], v[14:17]
	v_mfma_f32_16x16x32_bf16 v[10:13], v[138:141], v[190:193], v[10:13]
	v_mfma_f32_16x16x32_bf16 v[54:57], v[146:149], v[162:165], v[54:57]
	v_mfma_f32_16x16x32_bf16 v[50:53], v[154:157], v[162:165], v[50:53]
	v_mfma_f32_16x16x32_bf16 v[38:41], v[146:149], v[170:173], v[38:41]
	v_mfma_f32_16x16x32_bf16 v[34:37], v[154:157], v[170:173], v[34:37]
	v_mfma_f32_16x16x32_bf16 v[22:25], v[146:149], v[178:181], v[22:25]
	v_mfma_f32_16x16x32_bf16 v[18:21], v[154:157], v[178:181], v[18:21]
	v_mfma_f32_16x16x32_bf16 v[6:9], v[146:149], v[186:189], v[6:9]
	v_mfma_f32_16x16x32_bf16 v[2:5], v[154:157], v[186:189], v[2:5]
	v_mfma_f32_16x16x32_bf16 v[54:57], v[150:153], v[166:169], v[54:57]
	v_mfma_f32_16x16x32_bf16 v[50:53], v[158:161], v[166:169], v[50:53]
	v_mfma_f32_16x16x32_bf16 v[38:41], v[150:153], v[174:177], v[38:41]
	v_mfma_f32_16x16x32_bf16 v[34:37], v[158:161], v[174:177], v[34:37]
	s_setprio 2
	s_barrier
	v_mfma_f32_16x16x32_bf16 v[22:25], v[150:153], v[182:185], v[22:25]
	v_mfma_f32_16x16x32_bf16 v[18:21], v[158:161], v[182:185], v[18:21]
	v_mfma_f32_16x16x32_bf16 v[6:9], v[150:153], v[190:193], v[6:9]
	v_mfma_f32_16x16x32_bf16 v[2:5], v[158:161], v[190:193], v[2:5]
	s_setprio 0
	s_nop 0
	s_add_i32 s48, 0, 0x18000
	s_add_i32 s49, 0, 0x1c000
	v_add_u32_e32 v138, s48, v230
	v_add_u32_e32 v158, s49, v230
	ds_read_b128 v[114:117], v138
	ds_read_b128 v[118:121], v138 offset:1024
	ds_read_b128 v[130:133], v138 offset:2048
	ds_read_b128 v[138:141], v138 offset:3072
	ds_read_b128 v[146:149], v158
	ds_read_b128 v[150:153], v158 offset:1024
	ds_read_b128 v[154:157], v158 offset:2048
	ds_read_b128 v[158:161], v158 offset:3072
	s_add_u32 s34, s34, 0x40000
	s_addc_u32 s35, s35, 0
	s_mov_b32 m0, s38
	v_lshl_add_u64 v[214:215], s[34:35], 0, v[194:195]
	ds_read_b128 v[162:165], v234 offset:32768
	ds_read_b128 v[166:169], v234 offset:33792
	ds_read_b128 v[170:173], v234 offset:34816
	ds_read_b128 v[174:177], v234 offset:35840
	ds_read_b128 v[178:181], v234 offset:36864
	ds_read_b128 v[182:185], v234 offset:37888
	ds_read_b128 v[186:189], v234 offset:38912
	ds_read_b128 v[190:193], v234 offset:39936
	global_load_lds_dwordx4 v[214:215], off
	v_lshl_add_u64 v[214:215], s[34:35], 0, v[198:199]
	s_mov_b32 m0, s39
	s_nop 0
	global_load_lds_dwordx4 v[214:215], off
	s_waitcnt vmcnt(8)
	s_waitcnt lgkmcnt(0)
	s_barrier
	s_setprio 1
	v_mfma_f32_16x16x32_bf16 v[142:145], v[114:117], v[162:165], v[142:145]
	v_mfma_f32_16x16x32_bf16 v[134:137], v[130:133], v[162:165], v[134:137]
	v_mfma_f32_16x16x32_bf16 v[110:113], v[114:117], v[170:173], v[110:113]
	v_mfma_f32_16x16x32_bf16 v[106:109], v[130:133], v[170:173], v[106:109]
	v_mfma_f32_16x16x32_bf16 v[94:97], v[114:117], v[178:181], v[94:97]
	v_mfma_f32_16x16x32_bf16 v[90:93], v[130:133], v[178:181], v[90:93]
	v_mfma_f32_16x16x32_bf16 v[78:81], v[114:117], v[186:189], v[78:81]
	v_mfma_f32_16x16x32_bf16 v[74:77], v[130:133], v[186:189], v[74:77]
	v_mfma_f32_16x16x32_bf16 v[142:145], v[118:121], v[166:169], v[142:145]
	v_mfma_f32_16x16x32_bf16 v[134:137], v[138:141], v[166:169], v[134:137]
	v_mfma_f32_16x16x32_bf16 v[110:113], v[118:121], v[174:177], v[110:113]
	v_mfma_f32_16x16x32_bf16 v[106:109], v[138:141], v[174:177], v[106:109]
	v_mfma_f32_16x16x32_bf16 v[94:97], v[118:121], v[182:185], v[94:97]
	v_mfma_f32_16x16x32_bf16 v[90:93], v[138:141], v[182:185], v[90:93]
	v_mfma_f32_16x16x32_bf16 v[78:81], v[118:121], v[190:193], v[78:81]
	v_mfma_f32_16x16x32_bf16 v[74:77], v[138:141], v[190:193], v[74:77]
	v_mfma_f32_16x16x32_bf16 v[126:129], v[146:149], v[162:165], v[126:129]
	v_mfma_f32_16x16x32_bf16 v[122:125], v[154:157], v[162:165], v[122:125]
	v_mfma_f32_16x16x32_bf16 v[102:105], v[146:149], v[170:173], v[102:105]
	v_mfma_f32_16x16x32_bf16 v[98:101], v[154:157], v[170:173], v[98:101]
	v_mfma_f32_16x16x32_bf16 v[86:89], v[146:149], v[178:181], v[86:89]
	v_mfma_f32_16x16x32_bf16 v[82:85], v[154:157], v[178:181], v[82:85]
	v_mfma_f32_16x16x32_bf16 v[70:73], v[146:149], v[186:189], v[70:73]
	v_mfma_f32_16x16x32_bf16 v[66:69], v[154:157], v[186:189], v[66:69]
	v_mfma_f32_16x16x32_bf16 v[126:129], v[150:153], v[166:169], v[126:129]
	v_mfma_f32_16x16x32_bf16 v[122:125], v[158:161], v[166:169], v[122:125]
	v_mfma_f32_16x16x32_bf16 v[102:105], v[150:153], v[174:177], v[102:105]
	v_mfma_f32_16x16x32_bf16 v[98:101], v[158:161], v[174:177], v[98:101]
	s_setprio 2
	s_barrier
	v_mfma_f32_16x16x32_bf16 v[86:89], v[150:153], v[182:185], v[86:89]
	v_mfma_f32_16x16x32_bf16 v[82:85], v[158:161], v[182:185], v[82:85]
	v_mfma_f32_16x16x32_bf16 v[70:73], v[150:153], v[190:193], v[70:73]
	v_mfma_f32_16x16x32_bf16 v[66:69], v[158:161], v[190:193], v[66:69]
	s_setprio 0
	s_nop 0
	s_add_i32 s34, s48, s33
	v_lshl_add_u64 v[206:207], v[206:207], 0, s[8:9]
	s_mov_b32 m0, s34
	ds_read_b128 v[162:165], v234 offset:49152
	ds_read_b128 v[166:169], v234 offset:50176
	ds_read_b128 v[170:173], v234 offset:51200
	ds_read_b128 v[174:177], v234 offset:52224
	ds_read_b128 v[178:181], v234 offset:53248
	ds_read_b128 v[182:185], v234 offset:54272
	ds_read_b128 v[186:189], v234 offset:55296
	ds_read_b128 v[190:193], v234 offset:56320
	global_load_lds_dwordx4 v[206:207], off
	s_add_i32 m0, s34, 0x2000
	s_add_u32 s30, s30, 0x40080
	v_lshl_add_u64 v[206:207], v[208:209], 0, s[8:9]
	s_addc_u32 s31, s31, 0
	s_add_i32 s34, s49, s33
	global_load_lds_dwordx4 v[206:207], off
	v_lshl_add_u64 v[206:207], s[30:31], 0, v[196:197]
	s_mov_b32 m0, s34
	s_nop 0
	global_load_lds_dwordx4 v[206:207], off
	v_lshl_add_u64 v[206:207], s[30:31], 0, v[200:201]
	s_add_i32 m0, s34, 0x2000
	s_nop 0
	global_load_lds_dwordx4 v[206:207], off
	v_lshl_add_u64 v[206:207], v[210:211], 0, s[8:9]
	s_mov_b32 m0, s40
	s_nop 0
	global_load_lds_dwordx4 v[206:207], off
	v_lshl_add_u64 v[206:207], v[212:213], 0, s[8:9]
	s_mov_b32 m0, s41
	s_nop 0
	global_load_lds_dwordx4 v[206:207], off
	s_waitcnt vmcnt(8)
	s_waitcnt lgkmcnt(0)
	s_barrier
	s_setprio 1
	v_mfma_f32_16x16x32_bf16 v[62:65], v[114:117], v[162:165], v[62:65]
	v_mfma_f32_16x16x32_bf16 v[58:61], v[130:133], v[162:165], v[58:61]
	v_mfma_f32_16x16x32_bf16 v[46:49], v[114:117], v[170:173], v[46:49]
	v_mfma_f32_16x16x32_bf16 v[42:45], v[130:133], v[170:173], v[42:45]
	v_mfma_f32_16x16x32_bf16 v[30:33], v[114:117], v[178:181], v[30:33]
	v_mfma_f32_16x16x32_bf16 v[26:29], v[130:133], v[178:181], v[26:29]
	v_mfma_f32_16x16x32_bf16 v[14:17], v[114:117], v[186:189], v[14:17]
	v_mfma_f32_16x16x32_bf16 v[10:13], v[130:133], v[186:189], v[10:13]
	v_mfma_f32_16x16x32_bf16 v[62:65], v[118:121], v[166:169], v[62:65]
	v_mfma_f32_16x16x32_bf16 v[58:61], v[138:141], v[166:169], v[58:61]
	v_mfma_f32_16x16x32_bf16 v[46:49], v[118:121], v[174:177], v[46:49]
	v_mfma_f32_16x16x32_bf16 v[42:45], v[138:141], v[174:177], v[42:45]
	v_mfma_f32_16x16x32_bf16 v[30:33], v[118:121], v[182:185], v[30:33]
	v_mfma_f32_16x16x32_bf16 v[26:29], v[138:141], v[182:185], v[26:29]
	v_mfma_f32_16x16x32_bf16 v[14:17], v[118:121], v[190:193], v[14:17]
	v_mfma_f32_16x16x32_bf16 v[10:13], v[138:141], v[190:193], v[10:13]
	v_mfma_f32_16x16x32_bf16 v[54:57], v[146:149], v[162:165], v[54:57]
	v_mfma_f32_16x16x32_bf16 v[50:53], v[154:157], v[162:165], v[50:53]
	v_mfma_f32_16x16x32_bf16 v[38:41], v[146:149], v[170:173], v[38:41]
	v_mfma_f32_16x16x32_bf16 v[34:37], v[154:157], v[170:173], v[34:37]
	v_mfma_f32_16x16x32_bf16 v[22:25], v[146:149], v[178:181], v[22:25]
	v_mfma_f32_16x16x32_bf16 v[18:21], v[154:157], v[178:181], v[18:21]
	v_mfma_f32_16x16x32_bf16 v[6:9], v[146:149], v[186:189], v[6:9]
	v_mfma_f32_16x16x32_bf16 v[2:5], v[154:157], v[186:189], v[2:5]
	v_mfma_f32_16x16x32_bf16 v[54:57], v[150:153], v[166:169], v[54:57]
	v_mfma_f32_16x16x32_bf16 v[50:53], v[158:161], v[166:169], v[50:53]
	v_mfma_f32_16x16x32_bf16 v[38:41], v[150:153], v[174:177], v[38:41]
	v_mfma_f32_16x16x32_bf16 v[34:37], v[158:161], v[174:177], v[34:37]
	s_setprio 2
	s_barrier
	v_mfma_f32_16x16x32_bf16 v[22:25], v[150:153], v[182:185], v[22:25]
	v_mfma_f32_16x16x32_bf16 v[18:21], v[158:161], v[182:185], v[18:21]
	v_mfma_f32_16x16x32_bf16 v[6:9], v[150:153], v[190:193], v[6:9]
	v_mfma_f32_16x16x32_bf16 v[2:5], v[158:161], v[190:193], v[2:5]
	s_setprio 0
	s_nop 0
	s_add_i32 s47, s47, 2
	s_add_u32 s28, s28, 0x100
	s_addc_u32 s29, s29, 0
	s_add_u32 s45, s45, 0x100
	s_addc_u32 s46, s46, 0
	s_cmp_gt_u32 s47, 13
	s_cbranch_scc0 .LBB0_760
	s_and_b64 vcc, exec, s[10:11]
	s_cbranch_vccz .LBB0_763
	s_barrier

.LBB0_939:
	s_lshl_b32 s2, s2, 5
	s_and_b32 s12, s2, 0x60
	s_mov_b64 s[2:3], 0x80
	s_add_i32 m0, s27, 0x18000
	v_lshl_add_u64 v[8:9], v[8:9], 0, s[2:3]
	s_lshl_b32 s9, s8, 13
	s_lshl_b32 s13, s12, 7
	s_waitcnt vmcnt(2)
	s_barrier
	global_load_lds_dwordx4 v[8:9], off
	v_lshl_add_u64 v[6:7], v[6:7], 0, s[2:3]
	s_add_i32 m0, s27, 0x1a000
	s_add_i32 s33, s27, 0x8000
	s_add_i32 s34, s27, 0xa000
	global_load_lds_dwordx4 v[6:7], off
	v_lshl_add_u64 v[2:3], v[2:3], 0, s[2:3]
	s_mov_b32 m0, s33
	s_add_u32 s10, s22, 0x40080
	global_load_lds_dwordx4 v[2:3], off
	v_lshl_add_u64 v[2:3], v[4:5], 0, s[2:3]
	s_mov_b32 m0, s34
	s_addc_u32 s11, s23, 0
	global_load_lds_dwordx4 v[2:3], off
	s_add_i32 m0, s27, 0x1c000
	v_lshl_add_u64 v[2:3], s[10:11], 0, v[134:135]
	global_load_lds_dwordx4 v[2:3], off
	v_lshl_add_u64 v[2:3], s[10:11], 0, v[130:131]
	s_add_i32 m0, s27, 0x1e000
	s_cmpk_lt_u32 s7, 0x100
	global_load_lds_dwordx4 v[2:3], off
	v_and_b32_e32 v2, 15, v12
	v_lshrrev_b32_e32 v3, 1, v12
	s_sext_i32_i16 s38, s6
	v_lshl_or_b32 v148, s8, 6, v2
	v_and_b32_e32 v3, 24, v3
	s_cselect_b64 s[6:7], -1, 0
	s_lshl_b32 s8, s8, 8
	v_lshlrev_b32_e32 v4, 1, v3
	s_add_i32 s8, s8, 0
	v_lshl_or_b32 v4, v2, 6, v4
	v_lshlrev_b32_e32 v2, 2, v2
	s_add_i32 s8, s8, 0x20400
	v_and_b32_e32 v5, 32, v2
	v_add_u32_e32 v150, s8, v2
	v_lshlrev_b32_e32 v2, 14, v15
	v_and_b32_e32 v2, 0xffff8000, v2
	v_or_b32_e32 v151, s12, v3
	v_lshl_add_u32 v2, v14, 11, v2
	v_and_b32_e32 v3, 1, v15
	v_lshl_or_b32 v2, v3, 6, v2
	s_mov_b64 s[10:11], 0x40080
	v_lshl_add_u32 v2, v16, 1, v2
	v_mov_b32_e32 v3, v135
	v_lshl_add_u64 v[138:139], v[2:3], 0, s[10:11]
	v_lshlrev_b32_e32 v2, 14, v10
	v_and_b32_e32 v2, 0xffff8000, v2
	v_lshl_add_u32 v2, v11, 11, v2
	v_and_b32_e32 v3, 1, v10
	s_waitcnt vmcnt(6)
	v_lshl_or_b32 v2, v3, 6, v2
	v_bitop3_b32 v6, v4, s9, v5 bitop3:0xde
	v_lshl_add_u32 v2, v13, 1, v2
	v_mov_b32_e32 v3, v135
	v_bitop3_b32 v149, v4, s13, v5 bitop3:0xde
	v_lshl_add_u64 v[140:141], v[2:3], 0, s[10:11]
	s_add_i32 s35, 0, 0x10000
	s_add_i32 s36, 0, 0x14000
	v_add_u32_e32 v152, 0, v6
	v_mov_b32_e32 v153, 0x358637bd
	s_movk_i32 s37, 0x1600
	s_barrier
	s_branch .LBB0_942

.LBB0_945:
	v_add_u32_e32 v147, s35, v149
	ds_read_b128 v[154:157], v147
	ds_read_b128 v[158:161], v147 offset:1024
	ds_read_b128 v[162:165], v147 offset:2048
	ds_read_b128 v[166:169], v147 offset:3072
	v_add_u32_e32 v147, s36, v149
	s_add_u32 s22, s18, s20
	ds_read_b128 v[170:173], v147
	ds_read_b128 v[174:177], v147 offset:1024
	ds_read_b128 v[178:181], v147 offset:2048
	ds_read_b128 v[182:185], v147 offset:3072
	s_addc_u32 s23, s19, s21
	s_add_u32 s22, s22, 0x100
	s_addc_u32 s23, s23, 0
	s_add_u32 s45, s42, s20
	s_addc_u32 s46, s43, s21
	s_cmpk_eq_i32 s20, 0x700
	s_cselect_b32 s25, s9, s23
	s_cselect_b32 s24, s39, s22
	s_cselect_b32 s23, s40, s46
	s_cselect_b32 s22, s41, s45
	v_lshl_add_u64 v[218:219], v[142:143], 0, s[20:21]
	s_add_i32 m0, s27, 0xc000
	ds_read_b128 v[186:189], v152
	ds_read_b128 v[190:193], v152 offset:1024
	ds_read_b128 v[194:197], v152 offset:2048
	ds_read_b128 v[198:201], v152 offset:3072
	ds_read_b128 v[202:205], v152 offset:4096
	ds_read_b128 v[206:209], v152 offset:5120
	ds_read_b128 v[210:213], v152 offset:6144
	ds_read_b128 v[214:217], v152 offset:7168
	global_load_lds_dwordx4 v[218:219], off
	v_lshl_add_u64 v[218:219], v[144:145], 0, s[20:21]
	s_add_i32 m0, s27, 0xe000
	s_nop 0
	global_load_lds_dwordx4 v[218:219], off
	s_waitcnt vmcnt(8)
	s_waitcnt lgkmcnt(0)
	s_barrier
	s_setprio 1
	v_mfma_f32_16x16x32_bf16 v[126:129], v[154:157], v[186:189], v[126:129]
	v_mfma_f32_16x16x32_bf16 v[118:121], v[162:165], v[186:189], v[118:121]
	v_mfma_f32_16x16x32_bf16 v[110:113], v[154:157], v[194:197], v[110:113]
	v_mfma_f32_16x16x32_bf16 v[102:105], v[162:165], v[194:197], v[102:105]
	v_mfma_f32_16x16x32_bf16 v[94:97], v[154:157], v[202:205], v[94:97]
	v_mfma_f32_16x16x32_bf16 v[86:89], v[162:165], v[202:205], v[86:89]
	v_mfma_f32_16x16x32_bf16 v[78:81], v[154:157], v[210:213], v[78:81]
	v_mfma_f32_16x16x32_bf16 v[70:73], v[162:165], v[210:213], v[70:73]
	v_mfma_f32_16x16x32_bf16 v[126:129], v[158:161], v[190:193], v[126:129]
	v_mfma_f32_16x16x32_bf16 v[118:121], v[166:169], v[190:193], v[118:121]
	v_mfma_f32_16x16x32_bf16 v[110:113], v[158:161], v[198:201], v[110:113]
	v_mfma_f32_16x16x32_bf16 v[102:105], v[166:169], v[198:201], v[102:105]
	v_mfma_f32_16x16x32_bf16 v[94:97], v[158:161], v[206:209], v[94:97]
	v_mfma_f32_16x16x32_bf16 v[86:89], v[166:169], v[206:209], v[86:89]
	v_mfma_f32_16x16x32_bf16 v[78:81], v[158:161], v[214:217], v[78:81]
	v_mfma_f32_16x16x32_bf16 v[70:73], v[166:169], v[214:217], v[70:73]
	v_mfma_f32_16x16x32_bf16 v[122:125], v[170:173], v[186:189], v[122:125]
	v_mfma_f32_16x16x32_bf16 v[114:117], v[178:181], v[186:189], v[114:117]
	v_mfma_f32_16x16x32_bf16 v[106:109], v[170:173], v[194:197], v[106:109]
	v_mfma_f32_16x16x32_bf16 v[98:101], v[178:181], v[194:197], v[98:101]
	v_mfma_f32_16x16x32_bf16 v[90:93], v[170:173], v[202:205], v[90:93]
	v_mfma_f32_16x16x32_bf16 v[82:85], v[178:181], v[202:205], v[82:85]
	v_mfma_f32_16x16x32_bf16 v[74:77], v[170:173], v[210:213], v[74:77]
	v_mfma_f32_16x16x32_bf16 v[66:69], v[178:181], v[210:213], v[66:69]
	v_mfma_f32_16x16x32_bf16 v[122:125], v[174:177], v[190:193], v[122:125]
	v_mfma_f32_16x16x32_bf16 v[114:117], v[182:185], v[190:193], v[114:117]
	v_mfma_f32_16x16x32_bf16 v[106:109], v[174:177], v[198:201], v[106:109]
	v_mfma_f32_16x16x32_bf16 v[98:101], v[182:185], v[198:201], v[98:101]
	s_setprio 2
	s_barrier
	v_mfma_f32_16x16x32_bf16 v[90:93], v[174:177], v[206:209], v[90:93]
	v_mfma_f32_16x16x32_bf16 v[82:85], v[182:185], v[206:209], v[82:85]
	v_mfma_f32_16x16x32_bf16 v[74:77], v[174:177], v[214:217], v[74:77]
	v_mfma_f32_16x16x32_bf16 v[66:69], v[182:185], v[214:217], v[66:69]
	s_setprio 0
	s_nop 0
	s_add_i32 s45, s35, s26
	v_lshl_add_u64 v[218:219], s[22:23], 0, v[134:135]
	s_mov_b32 m0, s45
	ds_read_b128 v[186:189], v152 offset:16384
	ds_read_b128 v[190:193], v152 offset:17408
	ds_read_b128 v[194:197], v152 offset:18432
	ds_read_b128 v[198:201], v152 offset:19456
	ds_read_b128 v[202:205], v152 offset:20480
	ds_read_b128 v[206:209], v152 offset:21504
	ds_read_b128 v[210:213], v152 offset:22528
	ds_read_b128 v[214:217], v152 offset:23552
	global_load_lds_dwordx4 v[218:219], off
	s_add_i32 m0, s45, 0x2000
	s_add_u32 s46, s22, 0x40000
	v_lshl_add_u64 v[220:221], s[22:23], 0, v[130:131]
	s_addc_u32 s47, s23, 0
	s_add_i32 s45, s36, s26
	global_load_lds_dwordx4 v[220:221], off
	v_lshl_add_u64 v[222:223], s[46:47], 0, v[134:135]
	s_mov_b32 m0, s45
	v_lshl_add_u64 v[224:225], s[24:25], 0, v[132:133]
	global_load_lds_dwordx4 v[222:223], off
	v_lshl_add_u64 v[222:223], s[46:47], 0, v[130:131]
	s_add_i32 m0, s45, 0x2000
	s_nop 0
	global_load_lds_dwordx4 v[222:223], off
	v_lshl_add_u64 v[222:223], s[24:25], 0, v[136:137]
	s_mov_b32 m0, s27
	s_nop 0
	global_load_lds_dwordx4 v[222:223], off
	s_mov_b32 m0, s28
	s_nop 0
	global_load_lds_dwordx4 v[224:225], off
	s_waitcnt vmcnt(8)
	s_waitcnt lgkmcnt(0)
	s_barrier
	s_setprio 1
	v_mfma_f32_16x16x32_bf16 v[62:65], v[154:157], v[186:189], v[62:65]
	v_mfma_f32_16x16x32_bf16 v[54:57], v[162:165], v[186:189], v[54:57]
	v_mfma_f32_16x16x32_bf16 v[46:49], v[154:157], v[194:197], v[46:49]
	v_mfma_f32_16x16x32_bf16 v[38:41], v[162:165], v[194:197], v[38:41]
	v_mfma_f32_16x16x32_bf16 v[30:33], v[154:157], v[202:205], v[30:33]
	v_mfma_f32_16x16x32_bf16 v[22:25], v[162:165], v[202:205], v[22:25]
	v_mfma_f32_16x16x32_bf16 v[14:17], v[154:157], v[210:213], v[14:17]
	v_mfma_f32_16x16x32_bf16 v[6:9], v[162:165], v[210:213], v[6:9]
	v_mfma_f32_16x16x32_bf16 v[62:65], v[158:161], v[190:193], v[62:65]
	v_mfma_f32_16x16x32_bf16 v[54:57], v[166:169], v[190:193], v[54:57]
	v_mfma_f32_16x16x32_bf16 v[46:49], v[158:161], v[198:201], v[46:49]
	v_mfma_f32_16x16x32_bf16 v[38:41], v[166:169], v[198:201], v[38:41]
	v_mfma_f32_16x16x32_bf16 v[30:33], v[158:161], v[206:209], v[30:33]
	v_mfma_f32_16x16x32_bf16 v[22:25], v[166:169], v[206:209], v[22:25]
	v_mfma_f32_16x16x32_bf16 v[14:17], v[158:161], v[214:217], v[14:17]
	v_mfma_f32_16x16x32_bf16 v[6:9], v[166:169], v[214:217], v[6:9]
	v_mfma_f32_16x16x32_bf16 v[58:61], v[170:173], v[186:189], v[58:61]
	v_mfma_f32_16x16x32_bf16 v[50:53], v[178:181], v[186:189], v[50:53]
	v_mfma_f32_16x16x32_bf16 v[42:45], v[170:173], v[194:197], v[42:45]
	v_mfma_f32_16x16x32_bf16 v[34:37], v[178:181], v[194:197], v[34:37]
	v_mfma_f32_16x16x32_bf16 v[26:29], v[170:173], v[202:205], v[26:29]
	v_mfma_f32_16x16x32_bf16 v[18:21], v[178:181], v[202:205], v[18:21]
	v_mfma_f32_16x16x32_bf16 v[10:13], v[170:173], v[210:213], v[10:13]
	v_mfma_f32_16x16x32_bf16 v[2:5], v[178:181], v[210:213], v[2:5]
	v_mfma_f32_16x16x32_bf16 v[58:61], v[174:177], v[190:193], v[58:61]
	v_mfma_f32_16x16x32_bf16 v[50:53], v[182:185], v[190:193], v[50:53]
	v_mfma_f32_16x16x32_bf16 v[42:45], v[174:177], v[198:201], v[42:45]
	v_mfma_f32_16x16x32_bf16 v[34:37], v[182:185], v[198:201], v[34:37]
	s_setprio 2
	s_barrier
	v_mfma_f32_16x16x32_bf16 v[26:29], v[174:177], v[206:209], v[26:29]
	v_mfma_f32_16x16x32_bf16 v[18:21], v[182:185], v[206:209], v[18:21]
	v_mfma_f32_16x16x32_bf16 v[10:13], v[174:177], v[214:217], v[10:13]
	v_mfma_f32_16x16x32_bf16 v[2:5], v[182:185], v[214:217], v[2:5]
	s_setprio 0
	s_nop 0
	s_add_i32 s45, 0, 0x18000
	v_add_u32_e32 v147, s45, v149
	s_add_i32 s46, 0, 0x1c000
	ds_read_b128 v[154:157], v147
	ds_read_b128 v[158:161], v147 offset:1024
	ds_read_b128 v[162:165], v147 offset:2048
	ds_read_b128 v[166:169], v147 offset:3072
	v_add_u32_e32 v147, s46, v149
	ds_read_b128 v[170:173], v147
	ds_read_b128 v[174:177], v147 offset:1024
	ds_read_b128 v[178:181], v147 offset:2048
	ds_read_b128 v[182:185], v147 offset:3072
	s_add_u32 s24, s24, 0x40000
	s_addc_u32 s25, s25, 0
	s_mov_b32 m0, s29
	v_lshl_add_u64 v[226:227], s[24:25], 0, v[136:137]
	ds_read_b128 v[186:189], v152 offset:32768
	ds_read_b128 v[190:193], v152 offset:33792
	ds_read_b128 v[194:197], v152 offset:34816
	ds_read_b128 v[198:201], v152 offset:35840
	ds_read_b128 v[202:205], v152 offset:36864
	ds_read_b128 v[206:209], v152 offset:37888
	ds_read_b128 v[210:213], v152 offset:38912
	ds_read_b128 v[214:217], v152 offset:39936
	global_load_lds_dwordx4 v[226:227], off
	v_lshl_add_u64 v[226:227], s[24:25], 0, v[132:133]
	s_mov_b32 m0, s30
	s_nop 0
	global_load_lds_dwordx4 v[226:227], off
	s_waitcnt vmcnt(8)
	s_waitcnt lgkmcnt(0)
	s_barrier
	s_setprio 1
	v_mfma_f32_16x16x32_bf16 v[126:129], v[154:157], v[186:189], v[126:129]
	v_mfma_f32_16x16x32_bf16 v[118:121], v[162:165], v[186:189], v[118:121]
	v_mfma_f32_16x16x32_bf16 v[110:113], v[154:157], v[194:197], v[110:113]
	v_mfma_f32_16x16x32_bf16 v[102:105], v[162:165], v[194:197], v[102:105]
	v_mfma_f32_16x16x32_bf16 v[94:97], v[154:157], v[202:205], v[94:97]
	v_mfma_f32_16x16x32_bf16 v[86:89], v[162:165], v[202:205], v[86:89]
	v_mfma_f32_16x16x32_bf16 v[78:81], v[154:157], v[210:213], v[78:81]
	v_mfma_f32_16x16x32_bf16 v[70:73], v[162:165], v[210:213], v[70:73]
	v_mfma_f32_16x16x32_bf16 v[126:129], v[158:161], v[190:193], v[126:129]
	v_mfma_f32_16x16x32_bf16 v[118:121], v[166:169], v[190:193], v[118:121]
	v_mfma_f32_16x16x32_bf16 v[110:113], v[158:161], v[198:201], v[110:113]
	v_mfma_f32_16x16x32_bf16 v[102:105], v[166:169], v[198:201], v[102:105]
	v_mfma_f32_16x16x32_bf16 v[94:97], v[158:161], v[206:209], v[94:97]
	v_mfma_f32_16x16x32_bf16 v[86:89], v[166:169], v[206:209], v[86:89]
	v_mfma_f32_16x16x32_bf16 v[78:81], v[158:161], v[214:217], v[78:81]
	v_mfma_f32_16x16x32_bf16 v[70:73], v[166:169], v[214:217], v[70:73]
	v_mfma_f32_16x16x32_bf16 v[122:125], v[170:173], v[186:189], v[122:125]
	v_mfma_f32_16x16x32_bf16 v[114:117], v[178:181], v[186:189], v[114:117]
	v_mfma_f32_16x16x32_bf16 v[106:109], v[170:173], v[194:197], v[106:109]
	v_mfma_f32_16x16x32_bf16 v[98:101], v[178:181], v[194:197], v[98:101]
	v_mfma_f32_16x16x32_bf16 v[90:93], v[170:173], v[202:205], v[90:93]
	v_mfma_f32_16x16x32_bf16 v[82:85], v[178:181], v[202:205], v[82:85]
	v_mfma_f32_16x16x32_bf16 v[74:77], v[170:173], v[210:213], v[74:77]
	v_mfma_f32_16x16x32_bf16 v[66:69], v[178:181], v[210:213], v[66:69]
	v_mfma_f32_16x16x32_bf16 v[122:125], v[174:177], v[190:193], v[122:125]
	v_mfma_f32_16x16x32_bf16 v[114:117], v[182:185], v[190:193], v[114:117]
	v_mfma_f32_16x16x32_bf16 v[106:109], v[174:177], v[198:201], v[106:109]
	v_mfma_f32_16x16x32_bf16 v[98:101], v[182:185], v[198:201], v[98:101]
	s_setprio 2
	s_barrier
	v_mfma_f32_16x16x32_bf16 v[90:93], v[174:177], v[206:209], v[90:93]
	v_mfma_f32_16x16x32_bf16 v[82:85], v[182:185], v[206:209], v[82:85]
	v_mfma_f32_16x16x32_bf16 v[74:77], v[174:177], v[214:217], v[74:77]
	v_mfma_f32_16x16x32_bf16 v[66:69], v[182:185], v[214:217], v[66:69]
	s_setprio 0
	s_nop 0
	s_add_i32 s24, s45, s26
	v_lshl_add_u64 v[218:219], v[218:219], 0, s[2:3]
	s_mov_b32 m0, s24
	ds_read_b128 v[186:189], v152 offset:49152
	ds_read_b128 v[190:193], v152 offset:50176
	ds_read_b128 v[194:197], v152 offset:51200
	ds_read_b128 v[198:201], v152 offset:52224
	ds_read_b128 v[202:205], v152 offset:53248
	ds_read_b128 v[206:209], v152 offset:54272
	ds_read_b128 v[210:213], v152 offset:55296
	ds_read_b128 v[214:217], v152 offset:56320
	global_load_lds_dwordx4 v[218:219], off
	s_add_i32 m0, s24, 0x2000
	s_add_u32 s22, s22, 0x40080
	v_lshl_add_u64 v[218:219], v[220:221], 0, s[2:3]
	s_addc_u32 s23, s23, 0
	s_add_i32 s24, s46, s26
	global_load_lds_dwordx4 v[218:219], off
	v_lshl_add_u64 v[218:219], s[22:23], 0, v[134:135]
	s_mov_b32 m0, s24
	s_nop 0
	global_load_lds_dwordx4 v[218:219], off
	v_lshl_add_u64 v[218:219], s[22:23], 0, v[130:131]
	s_add_i32 m0, s24, 0x2000
	s_nop 0
	global_load_lds_dwordx4 v[218:219], off
	v_lshl_add_u64 v[218:219], v[222:223], 0, s[2:3]
	s_mov_b32 m0, s33
	s_nop 0
	global_load_lds_dwordx4 v[218:219], off
	v_lshl_add_u64 v[218:219], v[224:225], 0, s[2:3]
	s_mov_b32 m0, s34
	s_nop 0
	global_load_lds_dwordx4 v[218:219], off
	s_waitcnt vmcnt(8)
	s_waitcnt lgkmcnt(0)
	s_barrier
	s_setprio 1
	v_mfma_f32_16x16x32_bf16 v[62:65], v[154:157], v[186:189], v[62:65]
	v_mfma_f32_16x16x32_bf16 v[54:57], v[162:165], v[186:189], v[54:57]
	v_mfma_f32_16x16x32_bf16 v[46:49], v[154:157], v[194:197], v[46:49]
	v_mfma_f32_16x16x32_bf16 v[38:41], v[162:165], v[194:197], v[38:41]
	v_mfma_f32_16x16x32_bf16 v[30:33], v[154:157], v[202:205], v[30:33]
	v_mfma_f32_16x16x32_bf16 v[22:25], v[162:165], v[202:205], v[22:25]
	v_mfma_f32_16x16x32_bf16 v[14:17], v[154:157], v[210:213], v[14:17]
	v_mfma_f32_16x16x32_bf16 v[6:9], v[162:165], v[210:213], v[6:9]
	v_mfma_f32_16x16x32_bf16 v[62:65], v[158:161], v[190:193], v[62:65]
	v_mfma_f32_16x16x32_bf16 v[54:57], v[166:169], v[190:193], v[54:57]
	v_mfma_f32_16x16x32_bf16 v[46:49], v[158:161], v[198:201], v[46:49]
	v_mfma_f32_16x16x32_bf16 v[38:41], v[166:169], v[198:201], v[38:41]
	v_mfma_f32_16x16x32_bf16 v[30:33], v[158:161], v[206:209], v[30:33]
	v_mfma_f32_16x16x32_bf16 v[22:25], v[166:169], v[206:209], v[22:25]
	v_mfma_f32_16x16x32_bf16 v[14:17], v[158:161], v[214:217], v[14:17]
	v_mfma_f32_16x16x32_bf16 v[6:9], v[166:169], v[214:217], v[6:9]
	v_mfma_f32_16x16x32_bf16 v[58:61], v[170:173], v[186:189], v[58:61]
	v_mfma_f32_16x16x32_bf16 v[50:53], v[178:181], v[186:189], v[50:53]
	v_mfma_f32_16x16x32_bf16 v[42:45], v[170:173], v[194:197], v[42:45]
	v_mfma_f32_16x16x32_bf16 v[34:37], v[178:181], v[194:197], v[34:37]
	v_mfma_f32_16x16x32_bf16 v[26:29], v[170:173], v[202:205], v[26:29]
	v_mfma_f32_16x16x32_bf16 v[18:21], v[178:181], v[202:205], v[18:21]
	v_mfma_f32_16x16x32_bf16 v[10:13], v[170:173], v[210:213], v[10:13]
	v_mfma_f32_16x16x32_bf16 v[2:5], v[178:181], v[210:213], v[2:5]
	v_mfma_f32_16x16x32_bf16 v[58:61], v[174:177], v[190:193], v[58:61]
	v_mfma_f32_16x16x32_bf16 v[50:53], v[182:185], v[190:193], v[50:53]
	v_mfma_f32_16x16x32_bf16 v[42:45], v[174:177], v[198:201], v[42:45]
	v_mfma_f32_16x16x32_bf16 v[34:37], v[182:185], v[198:201], v[34:37]
	s_setprio 2
	s_barrier
	v_mfma_f32_16x16x32_bf16 v[26:29], v[174:177], v[206:209], v[26:29]
	v_mfma_f32_16x16x32_bf16 v[18:21], v[182:185], v[206:209], v[18:21]
	v_mfma_f32_16x16x32_bf16 v[10:13], v[174:177], v[214:217], v[10:13]
	v_mfma_f32_16x16x32_bf16 v[2:5], v[182:185], v[214:217], v[2:5]
	s_setprio 0
	s_nop 0
	s_add_i32 s44, s44, 2
	s_add_u32 s20, s20, 0x100
	s_addc_u32 s21, s21, 0
	s_cmp_gt_u32 s44, 13
	s_cbranch_scc1 .LBB0_948

.LBB0_1018:
	s_add_u32 s4, s70, s56
	s_addc_u32 s5, s71, s57
	s_add_u32 s59, s70, s2
	s_addc_u32 s60, s71, s3
	s_add_i32 s61, 0, 0x10000
	s_cmp_eq_u32 s58, 40
	s_cselect_b32 s31, s1, s5
	s_cselect_b32 s30, s0, s4
	s_cselect_b32 s5, s15, s60
	s_cselect_b32 s4, s14, s59
	s_add_i32 s59, 0, 0x14000
	v_add_u32_e32 v154, s61, v140
	v_add_u32_e32 v170, s59, v140
	ds_read_b128 v[142:145], v154
	ds_read_b128 v[146:149], v154 offset:1024
	ds_read_b128 v[150:153], v154 offset:2048
	ds_read_b128 v[154:157], v154 offset:3072
	ds_read_b128 v[158:161], v170
	ds_read_b128 v[162:165], v170 offset:1024
	ds_read_b128 v[166:169], v170 offset:2048
	ds_read_b128 v[170:173], v170 offset:3072
	v_lshl_add_u64 v[214:215], s[70:71], 0, v[136:137]
	s_add_i32 m0, s50, 0xc000
	ds_read_b128 v[174:177], v141
	ds_read_b128 v[178:181], v141 offset:1024
	ds_read_b128 v[182:185], v141 offset:2048
	ds_read_b128 v[186:189], v141 offset:3072
	ds_read_b128 v[190:193], v141 offset:4096
	ds_read_b128 v[194:197], v141 offset:5120
	ds_read_b128 v[198:201], v141 offset:6144
	ds_read_b128 v[202:205], v141 offset:7168
	global_load_lds_dwordx4 v[214:215], off
	v_lshl_add_u64 v[214:215], s[70:71], 0, v[138:139]
	s_add_i32 m0, s50, 0xe000
	s_nop 0
	global_load_lds_dwordx4 v[214:215], off
	s_waitcnt vmcnt(8)
	s_waitcnt lgkmcnt(0)
	s_barrier
	s_setprio 1
	v_mfma_f32_16x16x32_bf16 v[126:129], v[142:145], v[174:177], v[126:129]
	v_mfma_f32_16x16x32_bf16 v[122:125], v[150:153], v[174:177], v[122:125]
	v_mfma_f32_16x16x32_bf16 v[110:113], v[142:145], v[182:185], v[110:113]
	v_mfma_f32_16x16x32_bf16 v[106:109], v[150:153], v[182:185], v[106:109]
	v_mfma_f32_16x16x32_bf16 v[94:97], v[142:145], v[190:193], v[94:97]
	v_mfma_f32_16x16x32_bf16 v[90:93], v[150:153], v[190:193], v[90:93]
	v_mfma_f32_16x16x32_bf16 v[78:81], v[142:145], v[198:201], v[78:81]
	v_mfma_f32_16x16x32_bf16 v[74:77], v[150:153], v[198:201], v[74:77]
	v_mfma_f32_16x16x32_bf16 v[126:129], v[146:149], v[178:181], v[126:129]
	v_mfma_f32_16x16x32_bf16 v[122:125], v[154:157], v[178:181], v[122:125]
	v_mfma_f32_16x16x32_bf16 v[110:113], v[146:149], v[186:189], v[110:113]
	v_mfma_f32_16x16x32_bf16 v[106:109], v[154:157], v[186:189], v[106:109]
	v_mfma_f32_16x16x32_bf16 v[94:97], v[146:149], v[194:197], v[94:97]
	v_mfma_f32_16x16x32_bf16 v[90:93], v[154:157], v[194:197], v[90:93]
	v_mfma_f32_16x16x32_bf16 v[78:81], v[146:149], v[202:205], v[78:81]
	v_mfma_f32_16x16x32_bf16 v[74:77], v[154:157], v[202:205], v[74:77]
	v_mfma_f32_16x16x32_bf16 v[118:121], v[158:161], v[174:177], v[118:121]
	v_mfma_f32_16x16x32_bf16 v[114:117], v[166:169], v[174:177], v[114:117]
	v_mfma_f32_16x16x32_bf16 v[102:105], v[158:161], v[182:185], v[102:105]
	v_mfma_f32_16x16x32_bf16 v[98:101], v[166:169], v[182:185], v[98:101]
	v_mfma_f32_16x16x32_bf16 v[86:89], v[158:161], v[190:193], v[86:89]
	v_mfma_f32_16x16x32_bf16 v[82:85], v[166:169], v[190:193], v[82:85]
	v_mfma_f32_16x16x32_bf16 v[70:73], v[158:161], v[198:201], v[70:73]
	v_mfma_f32_16x16x32_bf16 v[66:69], v[166:169], v[198:201], v[66:69]
	v_mfma_f32_16x16x32_bf16 v[118:121], v[162:165], v[178:181], v[118:121]
	v_mfma_f32_16x16x32_bf16 v[114:117], v[170:173], v[178:181], v[114:117]
	v_mfma_f32_16x16x32_bf16 v[102:105], v[162:165], v[186:189], v[102:105]
	v_mfma_f32_16x16x32_bf16 v[98:101], v[170:173], v[186:189], v[98:101]
	s_setprio 2
	s_barrier
	v_mfma_f32_16x16x32_bf16 v[86:89], v[162:165], v[194:197], v[86:89]
	v_mfma_f32_16x16x32_bf16 v[82:85], v[170:173], v[194:197], v[82:85]
	v_mfma_f32_16x16x32_bf16 v[70:73], v[162:165], v[202:205], v[70:73]
	v_mfma_f32_16x16x32_bf16 v[66:69], v[170:173], v[202:205], v[66:69]
	s_setprio 0
	s_nop 0
	s_add_i32 s60, s61, s39
	v_lshl_add_u64 v[214:215], s[4:5], 0, v[130:131]
	s_mov_b32 m0, s60
	ds_read_b128 v[174:177], v141 offset:16384
	ds_read_b128 v[178:181], v141 offset:17408
	ds_read_b128 v[182:185], v141 offset:18432
	ds_read_b128 v[186:189], v141 offset:19456
	ds_read_b128 v[190:193], v141 offset:20480
	ds_read_b128 v[194:197], v141 offset:21504
	ds_read_b128 v[198:201], v141 offset:22528
	ds_read_b128 v[202:205], v141 offset:23552
	global_load_lds_dwordx4 v[214:215], off
	s_add_i32 m0, s60, 0x2000
	s_add_u32 s60, s4, 0xb0000
	v_lshl_add_u64 v[216:217], s[4:5], 0, v[134:135]
	s_addc_u32 s61, s5, 0
	s_add_i32 s59, s59, s39
	global_load_lds_dwordx4 v[216:217], off
	v_lshl_add_u64 v[218:219], s[60:61], 0, v[130:131]
	s_mov_b32 m0, s59
	v_lshl_add_u64 v[220:221], s[30:31], 0, v[134:135]
	global_load_lds_dwordx4 v[218:219], off
	v_lshl_add_u64 v[218:219], s[60:61], 0, v[134:135]
	s_add_i32 m0, s59, 0x2000
	s_nop 0
	global_load_lds_dwordx4 v[218:219], off
	v_lshl_add_u64 v[218:219], s[30:31], 0, v[130:131]
	s_mov_b32 m0, s50
	s_nop 0
	global_load_lds_dwordx4 v[218:219], off
	s_mov_b32 m0, s51
	s_nop 0
	global_load_lds_dwordx4 v[220:221], off
	s_waitcnt vmcnt(8)
	s_waitcnt lgkmcnt(0)
	s_barrier
	s_setprio 1
	v_mfma_f32_16x16x32_bf16 v[62:65], v[142:145], v[174:177], v[62:65]
	v_mfma_f32_16x16x32_bf16 v[58:61], v[150:153], v[174:177], v[58:61]
	v_mfma_f32_16x16x32_bf16 v[46:49], v[142:145], v[182:185], v[46:49]
	v_mfma_f32_16x16x32_bf16 v[42:45], v[150:153], v[182:185], v[42:45]
	v_mfma_f32_16x16x32_bf16 v[30:33], v[142:145], v[190:193], v[30:33]
	v_mfma_f32_16x16x32_bf16 v[26:29], v[150:153], v[190:193], v[26:29]
	v_mfma_f32_16x16x32_bf16 v[14:17], v[142:145], v[198:201], v[14:17]
	v_mfma_f32_16x16x32_bf16 v[10:13], v[150:153], v[198:201], v[10:13]
	v_mfma_f32_16x16x32_bf16 v[62:65], v[146:149], v[178:181], v[62:65]
	v_mfma_f32_16x16x32_bf16 v[58:61], v[154:157], v[178:181], v[58:61]
	v_mfma_f32_16x16x32_bf16 v[46:49], v[146:149], v[186:189], v[46:49]
	v_mfma_f32_16x16x32_bf16 v[42:45], v[154:157], v[186:189], v[42:45]
	v_mfma_f32_16x16x32_bf16 v[30:33], v[146:149], v[194:197], v[30:33]
	v_mfma_f32_16x16x32_bf16 v[26:29], v[154:157], v[194:197], v[26:29]
	v_mfma_f32_16x16x32_bf16 v[14:17], v[146:149], v[202:205], v[14:17]
	v_mfma_f32_16x16x32_bf16 v[10:13], v[154:157], v[202:205], v[10:13]
	v_mfma_f32_16x16x32_bf16 v[54:57], v[158:161], v[174:177], v[54:57]
	v_mfma_f32_16x16x32_bf16 v[50:53], v[166:169], v[174:177], v[50:53]
	v_mfma_f32_16x16x32_bf16 v[38:41], v[158:161], v[182:185], v[38:41]
	v_mfma_f32_16x16x32_bf16 v[34:37], v[166:169], v[182:185], v[34:37]
	v_mfma_f32_16x16x32_bf16 v[22:25], v[158:161], v[190:193], v[22:25]
	v_mfma_f32_16x16x32_bf16 v[18:21], v[166:169], v[190:193], v[18:21]
	v_mfma_f32_16x16x32_bf16 v[6:9], v[158:161], v[198:201], v[6:9]
	v_mfma_f32_16x16x32_bf16 v[2:5], v[166:169], v[198:201], v[2:5]
	v_mfma_f32_16x16x32_bf16 v[54:57], v[162:165], v[178:181], v[54:57]
	v_mfma_f32_16x16x32_bf16 v[50:53], v[170:173], v[178:181], v[50:53]
	v_mfma_f32_16x16x32_bf16 v[38:41], v[162:165], v[186:189], v[38:41]
	v_mfma_f32_16x16x32_bf16 v[34:37], v[170:173], v[186:189], v[34:37]
	s_setprio 2
	s_barrier
	v_mfma_f32_16x16x32_bf16 v[22:25], v[162:165], v[194:197], v[22:25]
	v_mfma_f32_16x16x32_bf16 v[18:21], v[170:173], v[194:197], v[18:21]
	v_mfma_f32_16x16x32_bf16 v[6:9], v[162:165], v[202:205], v[6:9]
	v_mfma_f32_16x16x32_bf16 v[2:5], v[170:173], v[202:205], v[2:5]
	s_setprio 0
	s_nop 0
	s_add_i32 s59, 0, 0x18000
	s_add_i32 s60, 0, 0x1c000
	v_add_u32_e32 v154, s59, v140
	v_add_u32_e32 v170, s60, v140
	ds_read_b128 v[142:145], v154
	ds_read_b128 v[146:149], v154 offset:1024
	ds_read_b128 v[150:153], v154 offset:2048
	ds_read_b128 v[154:157], v154 offset:3072
	ds_read_b128 v[158:161], v170
	ds_read_b128 v[162:165], v170 offset:1024
	ds_read_b128 v[166:169], v170 offset:2048
	ds_read_b128 v[170:173], v170 offset:3072
	s_add_u32 s30, s30, 0xb0000
	s_addc_u32 s31, s31, 0
	s_mov_b32 m0, s52
	v_lshl_add_u64 v[222:223], s[30:31], 0, v[130:131]
	ds_read_b128 v[174:177], v141 offset:32768
	ds_read_b128 v[178:181], v141 offset:33792
	ds_read_b128 v[182:185], v141 offset:34816
	ds_read_b128 v[186:189], v141 offset:35840
	ds_read_b128 v[190:193], v141 offset:36864
	ds_read_b128 v[194:197], v141 offset:37888
	ds_read_b128 v[198:201], v141 offset:38912
	ds_read_b128 v[202:205], v141 offset:39936
	global_load_lds_dwordx4 v[222:223], off
	v_lshl_add_u64 v[222:223], s[30:31], 0, v[134:135]
	s_mov_b32 m0, s53
	s_nop 0
	global_load_lds_dwordx4 v[222:223], off
	s_waitcnt vmcnt(8)
	s_waitcnt lgkmcnt(0)
	s_barrier
	s_setprio 1
	v_mfma_f32_16x16x32_bf16 v[126:129], v[142:145], v[174:177], v[126:129]
	v_mfma_f32_16x16x32_bf16 v[122:125], v[150:153], v[174:177], v[122:125]
	v_mfma_f32_16x16x32_bf16 v[110:113], v[142:145], v[182:185], v[110:113]
	v_mfma_f32_16x16x32_bf16 v[106:109], v[150:153], v[182:185], v[106:109]
	v_mfma_f32_16x16x32_bf16 v[94:97], v[142:145], v[190:193], v[94:97]
	v_mfma_f32_16x16x32_bf16 v[90:93], v[150:153], v[190:193], v[90:93]
	v_mfma_f32_16x16x32_bf16 v[78:81], v[142:145], v[198:201], v[78:81]
	v_mfma_f32_16x16x32_bf16 v[74:77], v[150:153], v[198:201], v[74:77]
	v_mfma_f32_16x16x32_bf16 v[126:129], v[146:149], v[178:181], v[126:129]
	v_mfma_f32_16x16x32_bf16 v[122:125], v[154:157], v[178:181], v[122:125]
	v_mfma_f32_16x16x32_bf16 v[110:113], v[146:149], v[186:189], v[110:113]
	v_mfma_f32_16x16x32_bf16 v[106:109], v[154:157], v[186:189], v[106:109]
	v_mfma_f32_16x16x32_bf16 v[94:97], v[146:149], v[194:197], v[94:97]
	v_mfma_f32_16x16x32_bf16 v[90:93], v[154:157], v[194:197], v[90:93]
	v_mfma_f32_16x16x32_bf16 v[78:81], v[146:149], v[202:205], v[78:81]
	v_mfma_f32_16x16x32_bf16 v[74:77], v[154:157], v[202:205], v[74:77]
	v_mfma_f32_16x16x32_bf16 v[118:121], v[158:161], v[174:177], v[118:121]
	v_mfma_f32_16x16x32_bf16 v[114:117], v[166:169], v[174:177], v[114:117]
	v_mfma_f32_16x16x32_bf16 v[102:105], v[158:161], v[182:185], v[102:105]
	v_mfma_f32_16x16x32_bf16 v[98:101], v[166:169], v[182:185], v[98:101]
	v_mfma_f32_16x16x32_bf16 v[86:89], v[158:161], v[190:193], v[86:89]
	v_mfma_f32_16x16x32_bf16 v[82:85], v[166:169], v[190:193], v[82:85]
	v_mfma_f32_16x16x32_bf16 v[70:73], v[158:161], v[198:201], v[70:73]
	v_mfma_f32_16x16x32_bf16 v[66:69], v[166:169], v[198:201], v[66:69]
	v_mfma_f32_16x16x32_bf16 v[118:121], v[162:165], v[178:181], v[118:121]
	v_mfma_f32_16x16x32_bf16 v[114:117], v[170:173], v[178:181], v[114:117]
	v_mfma_f32_16x16x32_bf16 v[102:105], v[162:165], v[186:189], v[102:105]
	v_mfma_f32_16x16x32_bf16 v[98:101], v[170:173], v[186:189], v[98:101]
	s_setprio 2
	s_barrier
	v_mfma_f32_16x16x32_bf16 v[86:89], v[162:165], v[194:197], v[86:89]
	v_mfma_f32_16x16x32_bf16 v[82:85], v[170:173], v[194:197], v[82:85]
	v_mfma_f32_16x16x32_bf16 v[70:73], v[162:165], v[202:205], v[70:73]
	v_mfma_f32_16x16x32_bf16 v[66:69], v[170:173], v[202:205], v[66:69]
	s_setprio 0
	s_nop 0
	s_add_i32 s30, s59, s39
	v_lshl_add_u64 v[214:215], v[214:215], 0, s[24:25]
	s_mov_b32 m0, s30
	ds_read_b128 v[174:177], v141 offset:49152
	ds_read_b128 v[178:181], v141 offset:50176
	ds_read_b128 v[182:185], v141 offset:51200
	ds_read_b128 v[186:189], v141 offset:52224
	ds_read_b128 v[190:193], v141 offset:53248
	ds_read_b128 v[194:197], v141 offset:54272
	ds_read_b128 v[198:201], v141 offset:55296
	ds_read_b128 v[202:205], v141 offset:56320
	global_load_lds_dwordx4 v[214:215], off
	s_add_i32 m0, s30, 0x2000
	s_add_u32 s4, s4, 0xb0080
	v_lshl_add_u64 v[214:215], v[216:217], 0, s[24:25]
	s_addc_u32 s5, s5, 0
	s_add_i32 s30, s60, s39
	global_load_lds_dwordx4 v[214:215], off
	v_lshl_add_u64 v[214:215], s[4:5], 0, v[130:131]
	s_mov_b32 m0, s30
	s_nop 0
	global_load_lds_dwordx4 v[214:215], off
	v_lshl_add_u64 v[214:215], s[4:5], 0, v[134:135]
	s_add_i32 m0, s30, 0x2000
	s_nop 0
	global_load_lds_dwordx4 v[214:215], off
	v_lshl_add_u64 v[214:215], v[218:219], 0, s[24:25]
	s_mov_b32 m0, s54
	s_nop 0
	global_load_lds_dwordx4 v[214:215], off
	v_lshl_add_u64 v[214:215], v[220:221], 0, s[24:25]
	s_mov_b32 m0, s55
	s_nop 0
	global_load_lds_dwordx4 v[214:215], off
	s_waitcnt vmcnt(8)
	s_waitcnt lgkmcnt(0)
	s_barrier
	s_setprio 1
	v_mfma_f32_16x16x32_bf16 v[62:65], v[142:145], v[174:177], v[62:65]
	v_mfma_f32_16x16x32_bf16 v[58:61], v[150:153], v[174:177], v[58:61]
	v_mfma_f32_16x16x32_bf16 v[46:49], v[142:145], v[182:185], v[46:49]
	v_mfma_f32_16x16x32_bf16 v[42:45], v[150:153], v[182:185], v[42:45]
	v_mfma_f32_16x16x32_bf16 v[30:33], v[142:145], v[190:193], v[30:33]
	v_mfma_f32_16x16x32_bf16 v[26:29], v[150:153], v[190:193], v[26:29]
	v_mfma_f32_16x16x32_bf16 v[14:17], v[142:145], v[198:201], v[14:17]
	v_mfma_f32_16x16x32_bf16 v[10:13], v[150:153], v[198:201], v[10:13]
	v_mfma_f32_16x16x32_bf16 v[62:65], v[146:149], v[178:181], v[62:65]
	v_mfma_f32_16x16x32_bf16 v[58:61], v[154:157], v[178:181], v[58:61]
	v_mfma_f32_16x16x32_bf16 v[46:49], v[146:149], v[186:189], v[46:49]
	v_mfma_f32_16x16x32_bf16 v[42:45], v[154:157], v[186:189], v[42:45]
	v_mfma_f32_16x16x32_bf16 v[30:33], v[146:149], v[194:197], v[30:33]
	v_mfma_f32_16x16x32_bf16 v[26:29], v[154:157], v[194:197], v[26:29]
	v_mfma_f32_16x16x32_bf16 v[14:17], v[146:149], v[202:205], v[14:17]
	v_mfma_f32_16x16x32_bf16 v[10:13], v[154:157], v[202:205], v[10:13]
	v_mfma_f32_16x16x32_bf16 v[54:57], v[158:161], v[174:177], v[54:57]
	v_mfma_f32_16x16x32_bf16 v[50:53], v[166:169], v[174:177], v[50:53]
	v_mfma_f32_16x16x32_bf16 v[38:41], v[158:161], v[182:185], v[38:41]
	v_mfma_f32_16x16x32_bf16 v[34:37], v[166:169], v[182:185], v[34:37]
	v_mfma_f32_16x16x32_bf16 v[22:25], v[158:161], v[190:193], v[22:25]
	v_mfma_f32_16x16x32_bf16 v[18:21], v[166:169], v[190:193], v[18:21]
	v_mfma_f32_16x16x32_bf16 v[6:9], v[158:161], v[198:201], v[6:9]
	v_mfma_f32_16x16x32_bf16 v[2:5], v[166:169], v[198:201], v[2:5]
	v_mfma_f32_16x16x32_bf16 v[54:57], v[162:165], v[178:181], v[54:57]
	v_mfma_f32_16x16x32_bf16 v[50:53], v[170:173], v[178:181], v[50:53]
	v_mfma_f32_16x16x32_bf16 v[38:41], v[162:165], v[186:189], v[38:41]
	v_mfma_f32_16x16x32_bf16 v[34:37], v[170:173], v[186:189], v[34:37]
	s_setprio 2
	s_barrier
	v_mfma_f32_16x16x32_bf16 v[22:25], v[162:165], v[194:197], v[22:25]
	v_mfma_f32_16x16x32_bf16 v[18:21], v[170:173], v[194:197], v[18:21]
	v_mfma_f32_16x16x32_bf16 v[6:9], v[162:165], v[202:205], v[6:9]
	v_mfma_f32_16x16x32_bf16 v[2:5], v[170:173], v[202:205], v[2:5]
	s_setprio 0
	s_nop 0
	s_add_i32 s58, s58, 2
	s_add_u32 s56, s56, 0x100
	s_addc_u32 s57, s57, 0
	s_add_u32 s2, s2, 0x100
	s_addc_u32 s3, s3, 0
	v_lshl_add_u64 v[136:137], v[136:137], 0, s[28:29]
	s_cmp_lt_u32 s58, 42
	v_lshl_add_u64 v[138:139], v[138:139], 0, s[28:29]
	s_cbranch_scc1 .LBB0_1018
	s_waitcnt vmcnt(0)
	s_cmpk_gt_u32 s36, 0xff
	s_cbranch_scc1 .LBB0_1021
	s_barrier
